# all 4 weight transposes hand-rewritten with nt loads; nt on once-read f32 inputs (x in out-proj epilogue, cache copy, sample V); split-K units scheduled before the prompt tile on WGs 0-63
# speedup vs baseline: 1.0469x; 1.0212x over previous
.LBB0_17:
	s_or_b64 exec, exec, s[0:1]
	v_readfirstlane_b32 s0, v171
	s_lshr_b32 s1, s0, 6
	v_and_b32_e32 v170, 63, v171
	v_writelane_b32 v254, s0, 43
	s_nop 0
	v_readlane_b32 s0, v254, 0
	s_lshl_b32 s0, s0, 3
	v_writelane_b32 v254, s1, 44
	s_add_i32 s2, s1, s0
	s_lshl_b32 s0, s76, 3
	v_writelane_b32 v254, s0, 45
	s_cmpk_gt_i32 s2, 0x31ff
	s_nop 0
	v_writelane_b32 v254, s1, 46
	s_mov_b32 s0, s2
	v_writelane_b32 v254, s0, 47
	s_nop 1
	v_writelane_b32 v254, s1, 48
	s_cbranch_scc1 .LBB0_39
	s_movk_i32 s5, 0x1200
	s_movk_i32 s6, 0xa00
	v_readlane_b32 s7, v254, 45
	v_readlane_b32 s8, v254, 47
	v_readlane_b32 s2, v254, 44
	v_and_b32_e32 v1, 31, v170
	v_lshlrev_b32_e32 v1, 2, v1
	v_lshrrev_b32_e32 v0, 5, v170
	s_mulk_i32 s2, 0x2200
	v_mul_u32_u24_e32 v2, 0xc800, v0
	v_add_u32_e32 v2, v2, v1
	s_mov_b32 s3, 0x19000
	v_add_u32_e32 v3, s3, v2
	v_add_u32_e32 v4, s3, v3
	v_add_u32_e32 v5, s3, v4
	v_add_u32_e32 v6, s3, v5
	v_add_u32_e32 v7, s3, v6
	v_add_u32_e32 v8, s3, v7
	v_add_u32_e32 v9, s3, v8
	v_mul_u32_u24_e32 v16, 0x84, v0
	v_add3_u32 v10, s2, v16, v1
	v_and_b32_e32 v17, 7, v170
	v_lshrrev_b32_e32 v18, 3, v170
	v_mul_u32_u24_e32 v19, 0x420, v17
	v_lshlrev_b32_e32 v20, 2, v18
	v_add3_u32 v11, s2, v19, v20
	v_mul_u32_u24_e32 v21, 0x1000, v18
	v_lshl_add_u32 v12, v17, 4, v21
	s_mov_b32 s3, 0x8000
	v_add_u32_e32 v13, s3, v12
	v_add_u32_e32 v14, s3, v13
	v_add_u32_e32 v15, s3, v14
	s_mov_b32 s14, 0

.LBB0_36:
	s_mul_i32 s0, s3, 0x320000
	s_lshl_b32 s1, s2, 2
	s_add_u32 s0, s0, s1
	s_lshl_b32 s1, s9, 12
	s_lshl_b32 s2, s3, 7
	s_add_u32 s1, s1, s2
	v_readlane_b32 s20, v254, 18
	v_readlane_b32 s21, v254, 19
	v_readlane_b32 s16, v254, 2
	v_readlane_b32 s17, v254, 3
	s_add_u32 s20, s20, s0
	s_addc_u32 s21, s21, 0
	s_add_u32 s16, s16, s1
	s_addc_u32 s17, s17, 0
	s_add_u32 s22, s20, 0xc8000
	s_addc_u32 s23, s21, 0
	s_add_u32 s24, s22, 0xc8000
	s_addc_u32 s25, s23, 0
	s_add_u32 s26, s24, 0xc8000
	s_addc_u32 s27, s25, 0
	global_load_dword v32, v2, s[20:21] nt
	global_load_dword v33, v3, s[20:21] nt
	global_load_dword v34, v4, s[20:21] nt
	global_load_dword v35, v5, s[20:21] nt
	global_load_dword v36, v6, s[20:21] nt
	global_load_dword v37, v7, s[20:21] nt
	global_load_dword v38, v8, s[20:21] nt
	global_load_dword v39, v9, s[20:21] nt
	global_load_dword v40, v2, s[22:23] nt
	global_load_dword v41, v3, s[22:23] nt
	global_load_dword v42, v4, s[22:23] nt
	global_load_dword v43, v5, s[22:23] nt
	global_load_dword v44, v6, s[22:23] nt
	global_load_dword v45, v7, s[22:23] nt
	global_load_dword v46, v8, s[22:23] nt
	global_load_dword v47, v9, s[22:23] nt
	global_load_dword v48, v2, s[24:25] nt
	global_load_dword v49, v3, s[24:25] nt
	global_load_dword v50, v4, s[24:25] nt
	global_load_dword v51, v5, s[24:25] nt
	global_load_dword v52, v6, s[24:25] nt
	global_load_dword v53, v7, s[24:25] nt
	global_load_dword v54, v8, s[24:25] nt
	global_load_dword v55, v9, s[24:25] nt
	global_load_dword v56, v2, s[26:27] nt
	global_load_dword v57, v3, s[26:27] nt
	global_load_dword v58, v4, s[26:27] nt
	global_load_dword v59, v5, s[26:27] nt
	global_load_dword v60, v6, s[26:27] nt
	global_load_dword v61, v7, s[26:27] nt
	global_load_dword v62, v8, s[26:27] nt
	global_load_dword v63, v9, s[26:27] nt
	s_mov_b32 s15, 1
	s_cmp_eq_u32 s14, 0
	s_cbranch_scc1 .Lp0a_ladder_first
.Lp0a_finish:
	s_waitcnt lgkmcnt(0)
	ds_read2_b32 v[16:17], v11 offset1:8
	ds_read2_b32 v[18:19], v11 offset0:33 offset1:41
	ds_read2_b32 v[20:21], v11 offset0:66 offset1:74
	ds_read2_b32 v[22:23], v11 offset0:99 offset1:107
	ds_read2_b32 v[24:25], v11 offset0:132 offset1:140
	ds_read2_b32 v[26:27], v11 offset0:165 offset1:173
	ds_read2_b32 v[28:29], v11 offset0:198 offset1:206
	ds_read2_b32 v[30:31], v11 offset0:231 offset1:239
	s_waitcnt lgkmcnt(0)
	v_cvt_pk_bf16_f32 v64, v16, v18
	v_cvt_pk_bf16_f32 v65, v20, v22
	v_cvt_pk_bf16_f32 v66, v24, v26
	v_cvt_pk_bf16_f32 v67, v28, v30
	v_cvt_pk_bf16_f32 v68, v17, v19
	v_cvt_pk_bf16_f32 v69, v21, v23
	v_cvt_pk_bf16_f32 v70, v25, v27
	v_cvt_pk_bf16_f32 v71, v29, v31
	ds_read2_b32 v[16:17], v11 offset0:16 offset1:24
	ds_read2_b32 v[18:19], v11 offset0:49 offset1:57
	ds_read2_b32 v[20:21], v11 offset0:82 offset1:90
	ds_read2_b32 v[22:23], v11 offset0:115 offset1:123
	ds_read2_b32 v[24:25], v11 offset0:148 offset1:156
	ds_read2_b32 v[26:27], v11 offset0:181 offset1:189
	ds_read2_b32 v[28:29], v11 offset0:214 offset1:222
	ds_read2_b32 v[30:31], v11 offset0:247 offset1:255
	global_store_dwordx4 v12, v[64:67], s[18:19]
	global_store_dwordx4 v13, v[68:71], s[18:19]
	s_nop 1
	s_waitcnt lgkmcnt(0)
	v_cvt_pk_bf16_f32 v64, v16, v18
	v_cvt_pk_bf16_f32 v65, v20, v22
	v_cvt_pk_bf16_f32 v66, v24, v26
	v_cvt_pk_bf16_f32 v67, v28, v30
	v_cvt_pk_bf16_f32 v68, v17, v19
	v_cvt_pk_bf16_f32 v69, v21, v23
	v_cvt_pk_bf16_f32 v70, v25, v27
	v_cvt_pk_bf16_f32 v71, v29, v31
	global_store_dwordx4 v14, v[64:67], s[18:19]
	global_store_dwordx4 v15, v[68:71], s[18:19]
	s_cmp_eq_u32 s15, 0
	s_cbranch_scc1 .LBB0_39
	s_waitcnt vmcnt(28)
	ds_write_b32 v10, v32
	ds_write_b32 v10, v33 offset:264
	ds_write_b32 v10, v34 offset:528
	ds_write_b32 v10, v35 offset:792
	ds_write_b32 v10, v36 offset:1056
	ds_write_b32 v10, v37 offset:1320
	ds_write_b32 v10, v38 offset:1584
	ds_write_b32 v10, v39 offset:1848
	s_waitcnt vmcnt(20)
	ds_write_b32 v10, v40 offset:2112
	ds_write_b32 v10, v41 offset:2376
	ds_write_b32 v10, v42 offset:2640
	ds_write_b32 v10, v43 offset:2904
	ds_write_b32 v10, v44 offset:3168
	ds_write_b32 v10, v45 offset:3432
	ds_write_b32 v10, v46 offset:3696
	ds_write_b32 v10, v47 offset:3960
	s_waitcnt vmcnt(12)
	ds_write_b32 v10, v48 offset:4224
	ds_write_b32 v10, v49 offset:4488
	ds_write_b32 v10, v50 offset:4752
	ds_write_b32 v10, v51 offset:5016
	ds_write_b32 v10, v52 offset:5280
	ds_write_b32 v10, v53 offset:5544
	ds_write_b32 v10, v54 offset:5808
	ds_write_b32 v10, v55 offset:6072
	s_waitcnt vmcnt(4)
	ds_write_b32 v10, v56 offset:6336
	ds_write_b32 v10, v57 offset:6600
	ds_write_b32 v10, v58 offset:6864
	ds_write_b32 v10, v59 offset:7128
	ds_write_b32 v10, v60 offset:7392
	ds_write_b32 v10, v61 offset:7656
	ds_write_b32 v10, v62 offset:7920
	ds_write_b32 v10, v63 offset:8184
	s_branch .Lp0a_common
.Lp0a_ladder_first:
	s_waitcnt vmcnt(24)
	ds_write_b32 v10, v32
	ds_write_b32 v10, v33 offset:264
	ds_write_b32 v10, v34 offset:528
	ds_write_b32 v10, v35 offset:792
	ds_write_b32 v10, v36 offset:1056
	ds_write_b32 v10, v37 offset:1320
	ds_write_b32 v10, v38 offset:1584
	ds_write_b32 v10, v39 offset:1848
	s_waitcnt vmcnt(16)
	ds_write_b32 v10, v40 offset:2112
	ds_write_b32 v10, v41 offset:2376
	ds_write_b32 v10, v42 offset:2640
	ds_write_b32 v10, v43 offset:2904
	ds_write_b32 v10, v44 offset:3168
	ds_write_b32 v10, v45 offset:3432
	ds_write_b32 v10, v46 offset:3696
	ds_write_b32 v10, v47 offset:3960
	s_waitcnt vmcnt(8)
	ds_write_b32 v10, v48 offset:4224
	ds_write_b32 v10, v49 offset:4488
	ds_write_b32 v10, v50 offset:4752
	ds_write_b32 v10, v51 offset:5016
	ds_write_b32 v10, v52 offset:5280
	ds_write_b32 v10, v53 offset:5544
	ds_write_b32 v10, v54 offset:5808
	ds_write_b32 v10, v55 offset:6072
	s_waitcnt vmcnt(0)
	ds_write_b32 v10, v56 offset:6336
	ds_write_b32 v10, v57 offset:6600
	ds_write_b32 v10, v58 offset:6864
	ds_write_b32 v10, v59 offset:7128
	ds_write_b32 v10, v60 offset:7392
	ds_write_b32 v10, v61 offset:7656
	ds_write_b32 v10, v62 offset:7920
	ds_write_b32 v10, v63 offset:8184
.Lp0a_common:
	s_mov_b64 s[18:19], s[16:17]
	s_mov_b32 s14, 1
	s_add_i32 s8, s8, s7
	s_cmp_lt_i32 s8, 0x3200
	s_cbranch_scc1 .LBB0_19
	s_mov_b32 s15, 0
	s_branch .Lp0a_finish

.LBB0_630:
	s_abs_i32 s2, s76
	s_waitcnt lgkmcnt(0)
	v_cvt_f32_u32_e32 v0, s2
	s_sub_i32 s4, 0, s2
	v_rcp_iflag_f32_e32 v0, v0
	s_nop 0
	v_mul_f32_e32 v0, 0x4f7ffffe, v0
	v_cvt_u32_f32_e32 v0, v0
	s_nop 0
	v_readfirstlane_b32 s5, v0
	s_mul_i32 s4, s4, s5
	s_mul_hi_u32 s4, s5, s4
	s_add_i32 s3, s5, s4
	s_mul_hi_u32 s4, s3, 0x6a4
	s_mul_i32 s4, s4, s2
	s_sub_i32 s4, 0x6a4, s4
	s_sub_i32 s5, s4, s2
	s_cmp_ge_u32 s4, s2
	s_cselect_b32 s4, s5, s4
	s_sub_i32 s5, s4, s2
	s_cmp_ge_u32 s4, s2
	v_writelane_b32 v254, s3, 62
	s_cselect_b32 s4, s5, s4
	v_writelane_b32 v254, s2, 63
	s_cmp_lg_u32 s4, 0
	s_cbranch_scc0 .LBB0_643
	v_readlane_b32 s2, v254, 0
	s_cmp_lt_i32 s2, s4
	s_cbranch_scc1 .LBB0_642
	v_readlane_b32 s2, v254, 0
	s_sub_i32 s5, s2, s4
	v_readlane_b32 s2, v254, 44
	s_sub_i32 s4, s76, s4
	s_mul_i32 s6, s2, 0x2200
	s_lshl_b32 s5, s5, 3
	s_add_i32 s10, s6, 0
	s_add_i32 s8, s5, s2
	s_lshl_b32 s9, s4, 3
	s_cmpk_gt_u32 s8, 0x7ff
	s_cbranch_scc1 .LBB0_637
	s_mov_b32 s4, s8
	s_mov_b32 s5, s9
	v_readlane_b32 s11, v254, 44
	v_and_b32_e32 v1, 31, v170
	v_lshlrev_b32_e32 v1, 2, v1
	v_lshrrev_b32_e32 v0, 5, v170
	s_mulk_i32 s11, 0x2200
	v_mul_u32_u24_e32 v2, 0x2000, v0
	v_add_u32_e32 v2, v2, v1
	s_mov_b32 s12, 0x4000
	v_add_u32_e32 v3, s12, v2
	v_add_u32_e32 v4, s12, v3
	v_add_u32_e32 v5, s12, v4
	v_add_u32_e32 v6, s12, v5
	v_add_u32_e32 v7, s12, v6
	v_add_u32_e32 v8, s12, v7
	v_add_u32_e32 v9, s12, v8
	v_mul_u32_u24_e32 v16, 0x84, v0
	v_add3_u32 v10, s11, v16, v1
	v_and_b32_e32 v17, 7, v170
	v_lshrrev_b32_e32 v18, 3, v170
	v_mul_u32_u24_e32 v19, 0x420, v17
	v_lshlrev_b32_e32 v20, 2, v18
	v_add3_u32 v11, s11, v19, v20
	v_mul_u32_u24_e32 v21, 0x1000, v18
	v_lshl_add_u32 v12, v17, 4, v21
	s_mov_b32 s12, 0x8000
	v_add_u32_e32 v13, s12, v12
	v_add_u32_e32 v14, s12, v13
	v_add_u32_e32 v15, s12, v14
	s_mov_b32 s13, 0
.Lp1b_top:
	s_and_b32 s11, s4, 0xffffffc0
	s_and_b32 s12, s4, 63
	s_lshl_b32 s2, s11, 13
	s_lshl_b32 s10, s12, 7
	s_add_u32 s2, s2, s10
	s_lshl_b32 s10, s12, 17
	s_lshl_b32 s11, s11, 1
	s_add_u32 s10, s10, s11
	s_add_u32 s10, s10, 0x3200000
	v_readlane_b32 s20, v254, 28
	v_readlane_b32 s21, v254, 29
	v_readlane_b32 s16, v254, 2
	v_readlane_b32 s17, v254, 3
	s_add_u32 s20, s20, s2
	s_addc_u32 s21, s21, 0
	s_add_u32 s16, s16, s10
	s_addc_u32 s17, s17, 0
	s_add_u32 s22, s20, 0x20000
	s_addc_u32 s23, s21, 0
	s_add_u32 s24, s22, 0x20000
	s_addc_u32 s25, s23, 0
	s_add_u32 s26, s24, 0x20000
	s_addc_u32 s27, s25, 0
	global_load_dword v32, v2, s[20:21] nt
	global_load_dword v33, v3, s[20:21] nt
	global_load_dword v34, v4, s[20:21] nt
	global_load_dword v35, v5, s[20:21] nt
	global_load_dword v36, v6, s[20:21] nt
	global_load_dword v37, v7, s[20:21] nt
	global_load_dword v38, v8, s[20:21] nt
	global_load_dword v39, v9, s[20:21] nt
	global_load_dword v40, v2, s[22:23] nt
	global_load_dword v41, v3, s[22:23] nt
	global_load_dword v42, v4, s[22:23] nt
	global_load_dword v43, v5, s[22:23] nt
	global_load_dword v44, v6, s[22:23] nt
	global_load_dword v45, v7, s[22:23] nt
	global_load_dword v46, v8, s[22:23] nt
	global_load_dword v47, v9, s[22:23] nt
	global_load_dword v48, v2, s[24:25] nt
	global_load_dword v49, v3, s[24:25] nt
	global_load_dword v50, v4, s[24:25] nt
	global_load_dword v51, v5, s[24:25] nt
	global_load_dword v52, v6, s[24:25] nt
	global_load_dword v53, v7, s[24:25] nt
	global_load_dword v54, v8, s[24:25] nt
	global_load_dword v55, v9, s[24:25] nt
	global_load_dword v56, v2, s[26:27] nt
	global_load_dword v57, v3, s[26:27] nt
	global_load_dword v58, v4, s[26:27] nt
	global_load_dword v59, v5, s[26:27] nt
	global_load_dword v60, v6, s[26:27] nt
	global_load_dword v61, v7, s[26:27] nt
	global_load_dword v62, v8, s[26:27] nt
	global_load_dword v63, v9, s[26:27] nt
	s_mov_b32 s14, 1
	s_cmp_eq_u32 s13, 0
	s_cbranch_scc1 .Lp1b_ladder_first
.Lp1b_finish:
	s_waitcnt lgkmcnt(0)
	ds_read2_b32 v[16:17], v11 offset1:8
	ds_read2_b32 v[18:19], v11 offset0:33 offset1:41
	ds_read2_b32 v[20:21], v11 offset0:66 offset1:74
	ds_read2_b32 v[22:23], v11 offset0:99 offset1:107
	ds_read2_b32 v[24:25], v11 offset0:132 offset1:140
	ds_read2_b32 v[26:27], v11 offset0:165 offset1:173
	ds_read2_b32 v[28:29], v11 offset0:198 offset1:206
	ds_read2_b32 v[30:31], v11 offset0:231 offset1:239
	s_waitcnt lgkmcnt(0)
	v_cvt_pk_bf16_f32 v64, v16, v18
	v_cvt_pk_bf16_f32 v65, v20, v22
	v_cvt_pk_bf16_f32 v66, v24, v26
	v_cvt_pk_bf16_f32 v67, v28, v30
	v_cvt_pk_bf16_f32 v68, v17, v19
	v_cvt_pk_bf16_f32 v69, v21, v23
	v_cvt_pk_bf16_f32 v70, v25, v27
	v_cvt_pk_bf16_f32 v71, v29, v31
	ds_read2_b32 v[16:17], v11 offset0:16 offset1:24
	ds_read2_b32 v[18:19], v11 offset0:49 offset1:57
	ds_read2_b32 v[20:21], v11 offset0:82 offset1:90
	ds_read2_b32 v[22:23], v11 offset0:115 offset1:123
	ds_read2_b32 v[24:25], v11 offset0:148 offset1:156
	ds_read2_b32 v[26:27], v11 offset0:181 offset1:189
	ds_read2_b32 v[28:29], v11 offset0:214 offset1:222
	ds_read2_b32 v[30:31], v11 offset0:247 offset1:255
	global_store_dwordx4 v12, v[64:67], s[18:19]
	global_store_dwordx4 v13, v[68:71], s[18:19]
	s_nop 1
	s_waitcnt lgkmcnt(0)
	v_cvt_pk_bf16_f32 v64, v16, v18
	v_cvt_pk_bf16_f32 v65, v20, v22
	v_cvt_pk_bf16_f32 v66, v24, v26
	v_cvt_pk_bf16_f32 v67, v28, v30
	v_cvt_pk_bf16_f32 v68, v17, v19
	v_cvt_pk_bf16_f32 v69, v21, v23
	v_cvt_pk_bf16_f32 v70, v25, v27
	v_cvt_pk_bf16_f32 v71, v29, v31
	global_store_dwordx4 v14, v[64:67], s[18:19]
	global_store_dwordx4 v15, v[68:71], s[18:19]
	s_cmp_eq_u32 s14, 0
	s_cbranch_scc1 .LBB0_637
	s_waitcnt vmcnt(28)
	ds_write_b32 v10, v32
	ds_write_b32 v10, v33 offset:264
	ds_write_b32 v10, v34 offset:528
	ds_write_b32 v10, v35 offset:792
	ds_write_b32 v10, v36 offset:1056
	ds_write_b32 v10, v37 offset:1320
	ds_write_b32 v10, v38 offset:1584
	ds_write_b32 v10, v39 offset:1848
	s_waitcnt vmcnt(20)
	ds_write_b32 v10, v40 offset:2112
	ds_write_b32 v10, v41 offset:2376
	ds_write_b32 v10, v42 offset:2640
	ds_write_b32 v10, v43 offset:2904
	ds_write_b32 v10, v44 offset:3168
	ds_write_b32 v10, v45 offset:3432
	ds_write_b32 v10, v46 offset:3696
	ds_write_b32 v10, v47 offset:3960
	s_waitcnt vmcnt(12)
	ds_write_b32 v10, v48 offset:4224
	ds_write_b32 v10, v49 offset:4488
	ds_write_b32 v10, v50 offset:4752
	ds_write_b32 v10, v51 offset:5016
	ds_write_b32 v10, v52 offset:5280
	ds_write_b32 v10, v53 offset:5544
	ds_write_b32 v10, v54 offset:5808
	ds_write_b32 v10, v55 offset:6072
	s_waitcnt vmcnt(4)
	ds_write_b32 v10, v56 offset:6336
	ds_write_b32 v10, v57 offset:6600
	ds_write_b32 v10, v58 offset:6864
	ds_write_b32 v10, v59 offset:7128
	ds_write_b32 v10, v60 offset:7392
	ds_write_b32 v10, v61 offset:7656
	ds_write_b32 v10, v62 offset:7920
	ds_write_b32 v10, v63 offset:8184
	s_branch .Lp1b_common

.Lp1b_common:
	s_mov_b64 s[18:19], s[16:17]
	s_mov_b32 s13, 1
	s_add_i32 s4, s4, s5
	s_cmp_lt_i32 s4, 0x800
	s_cbranch_scc1 .Lp1b_top
	s_mov_b32 s14, 0
	s_branch .Lp1b_finish
.LBB0_637:
	s_cmpk_gt_i32 s8, 0x2bff
	s_cbranch_scc1 .LBB0_642
	s_mov_b32 s4, s8
	s_mov_b32 s5, s9
	v_readlane_b32 s11, v254, 44
	v_and_b32_e32 v1, 31, v170
	v_lshlrev_b32_e32 v1, 2, v1
	v_lshrrev_b32_e32 v0, 5, v170
	s_mulk_i32 s11, 0x2200
	v_mul_u32_u24_e32 v2, 0xb000, v0
	v_add_u32_e32 v2, v2, v1
	s_mov_b32 s12, 0x16000
	v_add_u32_e32 v3, s12, v2
	v_add_u32_e32 v4, s12, v3
	v_add_u32_e32 v5, s12, v4
	v_add_u32_e32 v6, s12, v5
	v_add_u32_e32 v7, s12, v6
	v_add_u32_e32 v8, s12, v7
	v_add_u32_e32 v9, s12, v8
	v_mul_u32_u24_e32 v16, 0x84, v0
	v_add3_u32 v10, s11, v16, v1
	v_and_b32_e32 v17, 7, v170
	v_lshrrev_b32_e32 v18, 3, v170
	v_mul_u32_u24_e32 v19, 0x420, v17
	v_lshlrev_b32_e32 v20, 2, v18
	v_add3_u32 v11, s11, v19, v20
	v_mul_u32_u24_e32 v21, 0x1000, v18
	v_lshl_add_u32 v12, v17, 4, v21
	s_mov_b32 s12, 0x8000
	v_add_u32_e32 v13, s12, v12
	v_add_u32_e32 v14, s12, v13
	v_add_u32_e32 v15, s12, v14
	s_mov_b32 s13, 0
.Lp1c_top:
	s_mul_hi_u32 s11, s4, 0x2e8ba2e9
	s_lshr_b32 s11, s11, 6
	s_mul_i32 s12, s11, 0x160
	s_sub_i32 s12, s4, s12
	s_bfe_u32 s2, s12, 0x10002
	s_mul_i32 s2, s2, 0x1600
	s_lshr_b32 s10, s12, 3
	s_lshl_b32 s10, s10, 7
	s_add_u32 s2, s2, s10
	s_and_b32 s10, s12, 3
	s_lshl_b32 s10, s10, 5
	s_add_u32 s2, s2, s10
	s_lshl_b32 s2, s2, 2
	s_mul_i32 s10, s11, 0x2c0000
	s_add_u32 s2, s2, s10
	s_lshl_b32 s10, s12, 17
	s_lshl_b32 s11, s11, 7
	s_add_u32 s10, s10, s11
	s_add_u32 s10, s10, 0x3a00000
	v_readlane_b32 s20, v254, 32
	v_readlane_b32 s21, v254, 33
	v_readlane_b32 s16, v254, 2
	v_readlane_b32 s17, v254, 3
	s_add_u32 s20, s20, s2
	s_addc_u32 s21, s21, 0
	s_add_u32 s16, s16, s10
	s_addc_u32 s17, s17, 0
	s_add_u32 s22, s20, 0xb0000
	s_addc_u32 s23, s21, 0
	s_add_u32 s24, s22, 0xb0000
	s_addc_u32 s25, s23, 0
	s_add_u32 s26, s24, 0xb0000
	s_addc_u32 s27, s25, 0
	global_load_dword v32, v2, s[20:21] nt
	global_load_dword v33, v3, s[20:21] nt
	global_load_dword v34, v4, s[20:21] nt
	global_load_dword v35, v5, s[20:21] nt
	global_load_dword v36, v6, s[20:21] nt
	global_load_dword v37, v7, s[20:21] nt
	global_load_dword v38, v8, s[20:21] nt
	global_load_dword v39, v9, s[20:21] nt
	global_load_dword v40, v2, s[22:23] nt
	global_load_dword v41, v3, s[22:23] nt
	global_load_dword v42, v4, s[22:23] nt
	global_load_dword v43, v5, s[22:23] nt
	global_load_dword v44, v6, s[22:23] nt
	global_load_dword v45, v7, s[22:23] nt
	global_load_dword v46, v8, s[22:23] nt
	global_load_dword v47, v9, s[22:23] nt
	global_load_dword v48, v2, s[24:25] nt
	global_load_dword v49, v3, s[24:25] nt
	global_load_dword v50, v4, s[24:25] nt
	global_load_dword v51, v5, s[24:25] nt
	global_load_dword v52, v6, s[24:25] nt
	global_load_dword v53, v7, s[24:25] nt
	global_load_dword v54, v8, s[24:25] nt
	global_load_dword v55, v9, s[24:25] nt
	global_load_dword v56, v2, s[26:27] nt
	global_load_dword v57, v3, s[26:27] nt
	global_load_dword v58, v4, s[26:27] nt
	global_load_dword v59, v5, s[26:27] nt
	global_load_dword v60, v6, s[26:27] nt
	global_load_dword v61, v7, s[26:27] nt
	global_load_dword v62, v8, s[26:27] nt
	global_load_dword v63, v9, s[26:27] nt
	s_mov_b32 s14, 1
	s_cmp_eq_u32 s13, 0
	s_cbranch_scc1 .Lp1c_ladder_first

.Lp1c_common:
	s_mov_b64 s[18:19], s[16:17]
	s_mov_b32 s13, 1
	s_add_i32 s4, s4, s5
	s_cmp_lt_i32 s4, 0x2c00
	s_cbranch_scc1 .Lp1c_top
	s_mov_b32 s14, 0
	s_branch .Lp1c_finish

.LBB0_740:
	s_or_b64 exec, exec, vcc
	v_readlane_b32 s56, v254, 22
	v_lshlrev_b32_e32 v84, 2, v103
	v_readlane_b32 s58, v254, 24
	v_readlane_b32 s59, v254, 25
	s_waitcnt vmcnt(0)
	v_mfma_f32_32x32x16_bf16 v[64:79], v[88:91], v[80:83], v[64:79]
	v_cndmask_b32_e64 v18, v179, v18, s[48:49]
	v_cndmask_b32_e64 v19, v19, v179, s[50:51]
	v_readlane_b32 s57, v254, 23
	v_readlane_b32 s60, v254, 26
	global_load_dword v84, v84, s[58:59] nt
	s_nop 6
	v_cndmask_b32_e64 v69, v179, v16, s[44:45]
	v_cndmask_b32_e64 v70, v17, v179, s[46:47]
	v_and_b32_e32 v17, 64, v102
	v_xor_b32_e32 v16, 32, v102
	v_max_f32_e32 v68, v69, v69
	v_add_u32_e32 v17, 64, v17
	v_max_f32_e32 v68, 0xf149f2ca, v68
	v_cmp_lt_i32_e32 vcc, v16, v17
	v_max3_f32 v17, v68, v70, v18
	v_cndmask_b32_e64 v77, v66, v179, s[48:49]
	v_cndmask_b32_e32 v16, v102, v16, vcc
	v_lshlrev_b32_e32 v68, 2, v16
	v_max3_f32 v16, v17, v19, v20
	v_max3_f32 v16, v16, v21, v22
	v_max3_f32 v16, v16, v23, v24
	v_max3_f32 v16, v16, v25, v26
	v_max3_f32 v71, v16, v27, v28
	v_cndmask_b32_e64 v17, v64, v179, s[44:45]
	v_max3_f32 v64, v71, v29, v30
	v_max3_f32 v64, v64, v31, v32
	v_max3_f32 v64, v64, v33, v34
	v_max3_f32 v64, v64, v35, v36
	v_max3_f32 v64, v64, v37, v38
	v_max3_f32 v64, v64, v39, v40
	v_max3_f32 v64, v64, v41, v42
	v_max3_f32 v64, v64, v43, v44
	v_max3_f32 v64, v64, v45, v46
	v_max3_f32 v64, v64, v47, v48
	v_max3_f32 v64, v64, v49, v50
	v_max3_f32 v64, v64, v51, v52
	v_max3_f32 v64, v64, v53, v54
	v_max3_f32 v64, v64, v55, v56
	v_max3_f32 v64, v64, v57, v58
	v_max3_f32 v64, v64, v59, v60
	v_max3_f32 v64, v64, v61, v62
	v_max3_f32 v64, v64, v63, v0
	v_max3_f32 v64, v64, v1, v2
	v_max3_f32 v64, v64, v3, v4
	v_max3_f32 v64, v64, v5, v6
	v_max3_f32 v64, v64, v7, v8
	v_max3_f32 v64, v64, v9, v10
	v_max3_f32 v64, v64, v11, v12
	v_max3_f32 v64, v64, v13, v14
	v_cndmask_b32_e64 v16, v179, v65, s[46:47]
	v_max3_f32 v64, v64, v15, v17
	v_cndmask_b32_e64 v76, v179, v67, s[50:51]
	v_max3_f32 v64, v64, v16, v77
	v_max3_f32 v64, v64, v76, s17
	ds_bpermute_b32 v65, v68, v64
	v_readlane_b32 s61, v254, 27
	v_readlane_b32 s62, v254, 28
	v_readlane_b32 s63, v254, 29
	v_readlane_b32 s64, v254, 30
	s_waitcnt lgkmcnt(0)
	v_max_f32_e32 v65, v65, v65
	v_max_f32_e32 v64, v64, v65
	v_mul_f32_e32 v64, 0x3e38aa3b, v64
	v_readlane_b32 s65, v254, 31
	v_readlane_b32 s66, v254, 32
	v_readlane_b32 s67, v254, 33
	v_readlane_b32 s68, v254, 34
	v_readlane_b32 s69, v254, 35
	v_readlane_b32 s70, v254, 36
	v_readlane_b32 s71, v254, 37
	v_readlane_b32 s56, v254, 6
	v_readlane_b32 s62, v254, 12
	v_readlane_b32 s63, v254, 13
	v_lshlrev_b32_e32 v130, 2, v136
	v_readlane_b32 s57, v254, 7
	v_readlane_b32 s56, v254, 58
	v_readlane_b32 s57, v254, 59
	v_readlane_b32 s58, v254, 8
	v_readlane_b32 s59, v254, 9
	v_readlane_b32 s60, v254, 10
	v_readlane_b32 s61, v254, 11
	v_readlane_b32 s64, v254, 14
	v_readlane_b32 s65, v254, 15
	v_readlane_b32 s66, v254, 16
	v_readlane_b32 s67, v254, 17
	v_readlane_b32 s68, v254, 18
	s_waitcnt vmcnt(0)
	v_mul_f32_e32 v155, 0x3fb8aa3b, v84
	v_max_f32_e32 v181, v64, v155
	v_fma_f32 v64, v69, s18, -v181
	v_fma_f32 v65, v70, s18, -v181
	v_fma_f32 v66, v18, s18, -v181
	v_exp_f32_e32 v18, v64
	v_fma_f32 v67, v19, s18, -v181
	v_exp_f32_e32 v19, v65
	v_fma_f32 v69, v20, s18, -v181
	v_exp_f32_e32 v20, v66
	v_fma_f32 v70, v21, s18, -v181
	v_fma_f32 v26, v26, s18, -v181
	v_exp_f32_e32 v21, v67
	v_fma_f32 v71, v22, s18, -v181
	v_exp_f32_e32 v22, v69
	v_exp_f32_e32 v80, v26
	v_add_f32_e32 v26, 0, v18
	v_fma_f32 v72, v23, s18, -v181
	v_exp_f32_e32 v23, v70
	v_add_f32_e32 v26, v19, v26
	v_fma_f32 v73, v24, s18, -v181
	v_exp_f32_e32 v24, v71
	v_add_f32_e32 v26, v20, v26
	v_fma_f32 v74, v25, s18, -v181
	v_exp_f32_e32 v25, v72
	v_add_f32_e32 v26, v21, v26
	v_exp_f32_e32 v78, v73
	v_add_f32_e32 v26, v22, v26
	v_exp_f32_e32 v79, v74
	v_add_f32_e32 v26, v23, v26
	v_fma_f32 v27, v27, s18, -v181
	v_add_f32_e32 v26, v24, v26
	v_fma_f32 v28, v28, s18, -v181
	v_exp_f32_e32 v81, v27
	v_add_f32_e32 v26, v25, v26
	v_fma_f32 v29, v29, s18, -v181
	v_exp_f32_e32 v82, v28
	v_add_f32_e32 v26, v78, v26
	v_fma_f32 v30, v30, s18, -v181
	v_exp_f32_e32 v83, v29
	v_add_f32_e32 v26, v79, v26
	v_add_f32_e32 v26, v80, v26
	v_exp_f32_e32 v86, v30
	v_fma_f32 v27, v31, s18, -v181
	v_add_f32_e32 v26, v81, v26
	v_exp_f32_e32 v88, v27
	v_fma_f32 v27, v32, s18, -v181
	v_add_f32_e32 v26, v82, v26
	v_exp_f32_e32 v32, v27
	v_fma_f32 v27, v33, s18, -v181
	v_add_f32_e32 v26, v83, v26
	v_exp_f32_e32 v84, v27
	v_fma_f32 v27, v34, s18, -v181
	v_add_f32_e32 v26, v86, v26
	v_exp_f32_e32 v85, v27
	v_fma_f32 v27, v35, s18, -v181
	v_add_f32_e32 v26, v88, v26
	v_exp_f32_e32 v87, v27
	v_fma_f32 v27, v36, s18, -v181
	v_add_f32_e32 v26, v32, v26
	v_exp_f32_e32 v36, v27
	v_fma_f32 v27, v37, s18, -v181
	v_add_f32_e32 v26, v84, v26
	v_exp_f32_e32 v89, v27
	v_fma_f32 v27, v38, s18, -v181
	v_add_f32_e32 v26, v85, v26
	v_exp_f32_e32 v38, v27
	v_fma_f32 v27, v39, s18, -v181
	v_add_f32_e32 v26, v87, v26
	v_exp_f32_e32 v90, v27
	v_fma_f32 v27, v40, s18, -v181
	v_add_f32_e32 v26, v36, v26
	v_exp_f32_e32 v37, v27
	v_fma_f32 v27, v41, s18, -v181
	v_add_f32_e32 v26, v89, v26
	v_exp_f32_e32 v39, v27
	v_fma_f32 v27, v42, s18, -v181
	v_add_f32_e32 v26, v38, v26
	v_exp_f32_e32 v33, v27
	v_fma_f32 v27, v43, s18, -v181
	v_add_f32_e32 v26, v90, v26
	v_exp_f32_e32 v64, v27
	v_fma_f32 v27, v44, s18, -v181
	v_add_f32_e32 v26, v37, v26
	v_exp_f32_e32 v65, v27
	v_fma_f32 v27, v45, s18, -v181
	v_add_f32_e32 v26, v39, v26
	v_exp_f32_e32 v66, v27
	v_fma_f32 v27, v46, s18, -v181
	v_add_f32_e32 v26, v33, v26
	v_exp_f32_e32 v67, v27
	v_fma_f32 v27, v47, s18, -v181
	v_add_f32_e32 v26, v64, v26
	v_exp_f32_e32 v69, v27
	v_fma_f32 v27, v48, s18, -v181
	v_add_f32_e32 v26, v65, v26
	v_exp_f32_e32 v44, v27
	v_fma_f32 v27, v49, s18, -v181
	v_add_f32_e32 v26, v66, v26
	v_exp_f32_e32 v45, v27
	v_fma_f32 v27, v50, s18, -v181
	v_add_f32_e32 v26, v67, v26
	v_exp_f32_e32 v46, v27
	v_fma_f32 v27, v51, s18, -v181
	v_add_f32_e32 v26, v69, v26
	v_exp_f32_e32 v47, v27
	v_fma_f32 v27, v52, s18, -v181
	v_add_f32_e32 v26, v44, v26
	v_exp_f32_e32 v49, v27
	v_fma_f32 v27, v53, s18, -v181
	v_add_f32_e32 v26, v45, v26
	v_exp_f32_e32 v51, v27
	v_fma_f32 v27, v54, s18, -v181
	v_add_f32_e32 v26, v46, v26
	v_exp_f32_e32 v53, v27
	v_fma_f32 v27, v55, s18, -v181
	v_add_f32_e32 v26, v47, v26
	v_exp_f32_e32 v55, v27
	v_fma_f32 v27, v56, s18, -v181
	v_add_f32_e32 v26, v49, v26
	v_exp_f32_e32 v48, v27
	v_fma_f32 v27, v57, s18, -v181
	v_add_f32_e32 v26, v51, v26
	v_exp_f32_e32 v50, v27
	v_fma_f32 v27, v58, s18, -v181
	v_add_f32_e32 v26, v53, v26
	v_exp_f32_e32 v52, v27
	v_fma_f32 v27, v59, s18, -v181
	v_add_f32_e32 v26, v55, v26
	v_exp_f32_e32 v54, v27
	v_fma_f32 v27, v60, s18, -v181
	v_add_f32_e32 v26, v48, v26
	v_exp_f32_e32 v57, v27
	v_fma_f32 v27, v61, s18, -v181
	v_add_f32_e32 v26, v50, v26
	v_exp_f32_e32 v59, v27
	v_fma_f32 v27, v62, s18, -v181
	v_add_f32_e32 v26, v52, v26
	v_exp_f32_e32 v61, v27
	v_fma_f32 v27, v63, s18, -v181
	v_add_f32_e32 v26, v54, v26
	v_exp_f32_e32 v70, v27
	v_fma_f32 v0, v0, s18, -v181
	v_add_f32_e32 v26, v57, v26
	v_exp_f32_e32 v56, v0
	v_fma_f32 v1, v1, s18, -v181
	v_add_f32_e32 v0, v59, v26
	v_exp_f32_e32 v58, v1
	v_fma_f32 v1, v2, s18, -v181
	v_add_f32_e32 v0, v61, v0
	v_exp_f32_e32 v60, v1
	v_fma_f32 v1, v3, s18, -v181
	v_add_f32_e32 v0, v70, v0
	v_exp_f32_e32 v63, v1
	v_fma_f32 v1, v4, s18, -v181
	v_add_f32_e32 v0, v56, v0
	v_exp_f32_e32 v71, v1
	v_fma_f32 v1, v5, s18, -v181
	v_add_f32_e32 v0, v58, v0
	v_exp_f32_e32 v73, v1
	v_fma_f32 v1, v6, s18, -v181
	v_add_f32_e32 v0, v60, v0
	v_exp_f32_e32 v74, v1
	v_fma_f32 v1, v7, s18, -v181
	v_add_f32_e32 v0, v63, v0
	v_exp_f32_e32 v75, v1
	v_fma_f32 v1, v8, s18, -v181
	v_add_f32_e32 v0, v71, v0
	v_exp_f32_e32 v62, v1
	v_add_f32_e32 v0, v73, v0
	v_add_f32_e32 v0, v74, v0
	v_or_b32_e32 v34, s13, v137
	s_lshl_b32 s13, s14, 2
	v_add_f32_e32 v0, v75, v0
	s_add_u32 vcc_lo, s62, s13
	v_add_f32_e32 v91, v62, v0
	v_fma_f32 v0, v9, s18, -v181
	s_addc_u32 vcc_hi, s63, 0
	v_ashrrev_i32_e32 v35, 31, v34
	v_or_b32_e32 v4, 1, v34
	v_or_b32_e32 v8, 2, v34
	v_or_b32_e32 v28, 3, v34
	v_or_b32_e32 v42, 8, v34
	v_or_b32_e32 v94, 9, v34
	v_or_b32_e32 v104, 10, v34
	v_or_b32_e32 v108, 11, v34
	v_exp_f32_e32 v72, v0
	v_lshl_add_u64 v[40:41], vcc, 0, v[130:131]
	v_lshlrev_b64 v[0:1], 10, v[34:35]
	v_ashrrev_i32_e32 v5, 31, v4
	v_ashrrev_i32_e32 v9, 31, v8
	v_ashrrev_i32_e32 v29, 31, v28
	v_ashrrev_i32_e32 v43, 31, v42
	v_ashrrev_i32_e32 v95, 31, v94
	v_ashrrev_i32_e32 v105, 31, v104
	v_ashrrev_i32_e32 v109, 31, v108
	v_lshl_add_u64 v[2:3], v[40:41], 0, v[0:1]
	v_lshlrev_b64 v[4:5], 10, v[4:5]
	v_lshlrev_b64 v[8:9], 10, v[8:9]
	v_lshlrev_b64 v[28:29], 10, v[28:29]
	v_lshlrev_b64 v[92:93], 10, v[42:43]
	v_lshlrev_b64 v[94:95], 10, v[94:95]
	v_lshlrev_b64 v[104:105], 10, v[104:105]
	v_lshlrev_b64 v[108:109], 10, v[108:109]
	v_lshl_add_u64 v[6:7], v[40:41], 0, v[4:5]
	v_lshl_add_u64 v[26:27], v[40:41], 0, v[8:9]
	v_lshl_add_u64 v[30:31], v[40:41], 0, v[28:29]
	v_lshl_add_u64 v[42:43], v[40:41], 0, v[92:93]
	v_lshl_add_u64 v[98:99], v[40:41], 0, v[94:95]
	v_lshl_add_u64 v[106:107], v[40:41], 0, v[104:105]
	v_lshl_add_u64 v[110:111], v[40:41], 0, v[108:109]
	global_load_dword v35, v[2:3], off nt
	global_load_dword v143, v[6:7], off nt
	global_load_dword v144, v[26:27], off nt
	global_load_dword v145, v[30:31], off nt
	global_load_dword v146, v[42:43], off nt
	global_load_dword v147, v[98:99], off nt
	global_load_dword v148, v[106:107], off nt
	global_load_dword v149, v[110:111], off nt
	v_lshlrev_b32_e32 v130, 2, v124
	v_lshl_add_u64 v[42:43], vcc, 0, v[130:131]
	v_lshl_add_u64 v[0:1], v[42:43], 0, v[0:1]
	v_lshl_add_u64 v[2:3], v[42:43], 0, v[4:5]
	v_lshl_add_u64 v[4:5], v[42:43], 0, v[8:9]
	v_lshl_add_u64 v[6:7], v[42:43], 0, v[28:29]
	v_lshl_add_u64 v[8:9], v[42:43], 0, v[92:93]
	v_lshl_add_u64 v[26:27], v[42:43], 0, v[94:95]
	v_lshl_add_u64 v[28:29], v[42:43], 0, v[104:105]
	v_lshl_add_u64 v[30:31], v[42:43], 0, v[108:109]
	global_load_dword v130, v[0:1], off nt
	global_load_dword v150, v[2:3], off nt
	global_load_dword v151, v[4:5], off nt
	global_load_dword v152, v[6:7], off nt
	global_load_dword v153, v[8:9], off nt
	global_load_dword v182, v[26:27], off nt
	global_load_dword v183, v[28:29], off nt
	global_load_dword v184, v[30:31], off nt
	v_or_b32_e32 v0, 16, v34
	v_ashrrev_i32_e32 v1, 31, v0
	v_or_b32_e32 v4, 17, v34
	v_or_b32_e32 v8, 18, v34
	v_or_b32_e32 v28, 19, v34
	v_or_b32_e32 v92, 24, v34
	v_or_b32_e32 v98, 25, v34
	v_or_b32_e32 v106, 26, v34
	v_or_b32_e32 v110, 27, v34
	v_lshlrev_b64 v[0:1], 10, v[0:1]
	v_ashrrev_i32_e32 v5, 31, v4
	v_ashrrev_i32_e32 v9, 31, v8
	v_ashrrev_i32_e32 v29, 31, v28
	v_ashrrev_i32_e32 v93, 31, v92
	v_ashrrev_i32_e32 v99, 31, v98
	v_ashrrev_i32_e32 v107, 31, v106
	v_ashrrev_i32_e32 v111, 31, v110
	v_lshl_add_u64 v[2:3], v[40:41], 0, v[0:1]
	v_lshlrev_b64 v[4:5], 10, v[4:5]
	v_lshlrev_b64 v[8:9], 10, v[8:9]
	v_lshlrev_b64 v[28:29], 10, v[28:29]
	v_lshlrev_b64 v[92:93], 10, v[92:93]
	v_lshlrev_b64 v[98:99], 10, v[98:99]
	v_lshlrev_b64 v[106:107], 10, v[106:107]
	v_lshlrev_b64 v[110:111], 10, v[110:111]
	v_lshl_add_u64 v[6:7], v[40:41], 0, v[4:5]
	v_lshl_add_u64 v[26:27], v[40:41], 0, v[8:9]
	v_lshl_add_u64 v[30:31], v[40:41], 0, v[28:29]
	v_lshl_add_u64 v[94:95], v[40:41], 0, v[92:93]
	v_lshl_add_u64 v[104:105], v[40:41], 0, v[98:99]
	v_lshl_add_u64 v[108:109], v[40:41], 0, v[106:107]
	v_lshl_add_u64 v[112:113], v[40:41], 0, v[110:111]
	global_load_dword v185, v[2:3], off nt
	global_load_dword v186, v[6:7], off nt
	global_load_dword v187, v[26:27], off nt
	global_load_dword v188, v[30:31], off nt
	global_load_dword v189, v[94:95], off nt
	global_load_dword v190, v[104:105], off nt
	global_load_dword v191, v[108:109], off nt
	global_load_dword v192, v[112:113], off nt
	v_lshl_add_u64 v[0:1], v[42:43], 0, v[0:1]
	v_lshl_add_u64 v[2:3], v[42:43], 0, v[4:5]
	v_lshl_add_u64 v[4:5], v[42:43], 0, v[8:9]
	v_lshl_add_u64 v[6:7], v[42:43], 0, v[28:29]
	v_lshl_add_u64 v[8:9], v[42:43], 0, v[92:93]
	v_lshl_add_u64 v[26:27], v[42:43], 0, v[98:99]
	v_lshl_add_u64 v[28:29], v[42:43], 0, v[106:107]
	v_lshl_add_u64 v[30:31], v[42:43], 0, v[110:111]
	global_load_dword v193, v[0:1], off nt
	global_load_dword v194, v[2:3], off nt
	global_load_dword v195, v[4:5], off nt
	global_load_dword v196, v[6:7], off nt
	global_load_dword v197, v[8:9], off nt
	global_load_dword v198, v[26:27], off nt
	global_load_dword v199, v[28:29], off nt
	global_load_dword v200, v[30:31], off nt
	v_or_b32_e32 v0, 32, v34
	v_ashrrev_i32_e32 v1, 31, v0
	v_or_b32_e32 v4, 33, v34
	v_or_b32_e32 v8, 34, v34
	v_or_b32_e32 v28, 35, v34
	v_or_b32_e32 v92, 40, v34
	v_or_b32_e32 v98, 41, v34
	v_or_b32_e32 v106, 42, v34
	v_or_b32_e32 v110, 43, v34
	v_lshlrev_b64 v[0:1], 10, v[0:1]
	v_ashrrev_i32_e32 v5, 31, v4
	v_ashrrev_i32_e32 v9, 31, v8
	v_ashrrev_i32_e32 v29, 31, v28
	v_ashrrev_i32_e32 v93, 31, v92
	v_ashrrev_i32_e32 v99, 31, v98
	v_ashrrev_i32_e32 v107, 31, v106
	v_ashrrev_i32_e32 v111, 31, v110
	v_lshl_add_u64 v[2:3], v[40:41], 0, v[0:1]
	v_lshlrev_b64 v[4:5], 10, v[4:5]
	v_lshlrev_b64 v[8:9], 10, v[8:9]
	v_lshlrev_b64 v[28:29], 10, v[28:29]
	v_lshlrev_b64 v[92:93], 10, v[92:93]
	v_lshlrev_b64 v[98:99], 10, v[98:99]
	v_lshlrev_b64 v[106:107], 10, v[106:107]
	v_lshlrev_b64 v[110:111], 10, v[110:111]
	v_lshl_add_u64 v[6:7], v[40:41], 0, v[4:5]
	v_lshl_add_u64 v[26:27], v[40:41], 0, v[8:9]
	v_lshl_add_u64 v[30:31], v[40:41], 0, v[28:29]
	v_lshl_add_u64 v[94:95], v[40:41], 0, v[92:93]
	v_lshl_add_u64 v[104:105], v[40:41], 0, v[98:99]
	v_lshl_add_u64 v[108:109], v[40:41], 0, v[106:107]
	v_lshl_add_u64 v[112:113], v[40:41], 0, v[110:111]
	global_load_dword v201, v[2:3], off nt
	global_load_dword v202, v[6:7], off nt
	global_load_dword v203, v[26:27], off nt
	global_load_dword v204, v[30:31], off nt
	global_load_dword v205, v[94:95], off nt
	global_load_dword v206, v[104:105], off nt
	global_load_dword v207, v[108:109], off nt
	global_load_dword v208, v[112:113], off nt
	v_lshl_add_u64 v[0:1], v[42:43], 0, v[0:1]
	v_lshl_add_u64 v[2:3], v[42:43], 0, v[4:5]
	v_lshl_add_u64 v[4:5], v[42:43], 0, v[8:9]
	v_lshl_add_u64 v[6:7], v[42:43], 0, v[28:29]
	v_lshl_add_u64 v[8:9], v[42:43], 0, v[92:93]
	v_lshl_add_u64 v[26:27], v[42:43], 0, v[98:99]
	v_lshl_add_u64 v[28:29], v[42:43], 0, v[106:107]
	v_lshl_add_u64 v[30:31], v[42:43], 0, v[110:111]
	global_load_dword v209, v[0:1], off nt
	global_load_dword v221, v[2:3], off nt
	global_load_dword v222, v[4:5], off nt
	global_load_dword v223, v[6:7], off nt
	global_load_dword v224, v[8:9], off nt
	global_load_dword v225, v[26:27], off nt
	global_load_dword v226, v[28:29], off nt
	global_load_dword v227, v[30:31], off nt
	v_or_b32_e32 v0, 48, v34
	v_ashrrev_i32_e32 v1, 31, v0
	v_or_b32_e32 v2, 49, v34
	v_or_b32_e32 v4, 50, v34
	v_or_b32_e32 v6, 51, v34
	v_or_b32_e32 v8, 56, v34
	v_or_b32_e32 v26, 57, v34
	v_or_b32_e32 v28, 58, v34
	v_or_b32_e32 v30, 59, v34
	v_lshlrev_b64 v[108:109], 10, v[0:1]
	v_ashrrev_i32_e32 v3, 31, v2
	v_ashrrev_i32_e32 v5, 31, v4
	v_ashrrev_i32_e32 v7, 31, v6
	v_ashrrev_i32_e32 v9, 31, v8
	v_ashrrev_i32_e32 v27, 31, v26
	v_ashrrev_i32_e32 v29, 31, v28
	v_ashrrev_i32_e32 v31, 31, v30
	v_lshl_add_u64 v[0:1], v[40:41], 0, v[108:109]
	v_lshlrev_b64 v[110:111], 10, v[2:3]
	v_lshlrev_b64 v[112:113], 10, v[4:5]
	v_lshlrev_b64 v[114:115], 10, v[6:7]
	v_lshlrev_b64 v[116:117], 10, v[8:9]
	v_lshlrev_b64 v[118:119], 10, v[26:27]
	v_lshlrev_b64 v[120:121], 10, v[28:29]
	v_lshlrev_b64 v[122:123], 10, v[30:31]
	v_lshl_add_u64 v[2:3], v[40:41], 0, v[110:111]
	v_lshl_add_u64 v[4:5], v[40:41], 0, v[112:113]
	v_lshl_add_u64 v[6:7], v[40:41], 0, v[114:115]
	v_lshl_add_u64 v[8:9], v[40:41], 0, v[116:117]
	v_lshl_add_u64 v[26:27], v[40:41], 0, v[118:119]
	v_lshl_add_u64 v[28:29], v[40:41], 0, v[120:121]
	v_lshl_add_u64 v[30:31], v[40:41], 0, v[122:123]
	global_load_dword v228, v[0:1], off nt
	global_load_dword v229, v[2:3], off nt
	global_load_dword v230, v[4:5], off nt
	global_load_dword v231, v[6:7], off nt
	global_load_dword v232, v[8:9], off nt
	global_load_dword v233, v[26:27], off nt
	global_load_dword v234, v[28:29], off nt
	global_load_dword v235, v[30:31], off nt
	v_fma_f32 v1, v10, s18, -v181
	v_exp_f32_e32 v93, v1
	v_fma_f32 v1, v11, s18, -v181
	v_exp_f32_e32 v94, v1
	v_fma_f32 v1, v12, s18, -v181
	v_exp_f32_e32 v95, v1
	v_fma_f32 v1, v13, s18, -v181
	v_add_f32_e32 v0, v72, v91
	v_exp_f32_e32 v98, v1
	v_add_f32_e32 v0, v93, v0
	v_add_f32_e32 v0, v94, v0
	v_add_f32_e32 v0, v95, v0
	v_add_f32_e32 v8, v98, v0
	v_fma_f32 v0, v14, s18, -v181
	v_exp_f32_e32 v99, v0
	v_fma_f32 v0, v15, s18, -v181
	v_exp_f32_e32 v102, v0
	v_fma_f32 v0, v17, s18, -v181
	v_exp_f32_e32 v91, v0
	v_fma_f32 v0, v16, s18, -v181
	v_exp_f32_e32 v92, v0
	s_waitcnt vmcnt(54)
	v_cvt_pk_bf16_f32 v0, v35, v143
	s_waitcnt vmcnt(52)
	v_cvt_pk_bf16_f32 v1, v144, v145
	s_waitcnt vmcnt(50)
	v_cvt_pk_bf16_f32 v2, v146, v147
	s_waitcnt vmcnt(48)
	v_cvt_pk_bf16_f32 v3, v148, v149
	v_cvt_pk_bf16_f32 v4, v18, v19
	v_cvt_pk_bf16_f32 v5, v20, v21
	v_cvt_pk_bf16_f32 v6, v22, v23
	v_cvt_pk_bf16_f32 v7, v24, v25
	v_add_f32_e32 v8, v99, v8
	v_add_f32_e32 v8, v102, v8
	v_mfma_f32_32x32x16_bf16 v[16:31], v[0:3], v[4:7], 0
	s_waitcnt vmcnt(46)
	v_cvt_pk_bf16_f32 v0, v130, v150
	s_waitcnt vmcnt(44)
	v_cvt_pk_bf16_f32 v1, v151, v152
	s_waitcnt vmcnt(42)
	v_cvt_pk_bf16_f32 v2, v153, v182
	s_waitcnt vmcnt(40)
	v_cvt_pk_bf16_f32 v3, v183, v184
	s_waitcnt vmcnt(38)
	v_cvt_pk_bf16_f32 v104, v185, v186
	s_waitcnt vmcnt(36)
	v_cvt_pk_bf16_f32 v105, v187, v188
	s_waitcnt vmcnt(34)
	v_cvt_pk_bf16_f32 v106, v189, v190
	s_waitcnt vmcnt(32)
	v_cvt_pk_bf16_f32 v107, v191, v192
	v_add_f32_e32 v8, v91, v8
	v_add_f32_e32 v35, v92, v8
	v_mfma_f32_32x32x16_bf16 v[0:15], v[0:3], v[4:7], 0
	v_cvt_pk_bf16_f32 v78, v78, v79
	v_cvt_pk_bf16_f32 v79, v80, v81
	v_cvt_pk_bf16_f32 v80, v82, v83
	v_cvt_pk_bf16_f32 v81, v86, v88
	v_cvt_pk_bf16_f32 v82, v32, v84
	v_cvt_pk_bf16_f32 v83, v85, v87
	v_cvt_pk_bf16_f32 v84, v36, v89
	v_mfma_f32_32x32x16_bf16 v[16:31], v[104:107], v[78:81], v[16:31]
	s_waitcnt vmcnt(30)
	v_cvt_pk_bf16_f32 v104, v193, v194
	s_waitcnt vmcnt(28)
	v_cvt_pk_bf16_f32 v105, v195, v196
	s_waitcnt vmcnt(26)
	v_cvt_pk_bf16_f32 v106, v197, v198
	s_waitcnt vmcnt(24)
	v_cvt_pk_bf16_f32 v107, v199, v200
	s_waitcnt vmcnt(14)
	v_cvt_pk_bf16_f32 v86, v209, v221
	s_waitcnt vmcnt(12)
	v_cvt_pk_bf16_f32 v87, v222, v223
	s_waitcnt vmcnt(10)
	v_cvt_pk_bf16_f32 v88, v224, v225
	v_mfma_f32_32x32x16_bf16 v[0:15], v[104:107], v[78:81], v[0:15]
	v_cvt_pk_bf16_f32 v78, v201, v202
	v_cvt_pk_bf16_f32 v79, v203, v204
	v_cvt_pk_bf16_f32 v80, v205, v206
	v_cvt_pk_bf16_f32 v81, v207, v208
	s_waitcnt vmcnt(8)
	v_cvt_pk_bf16_f32 v89, v226, v227
	v_cvt_pk_bf16_f32 v85, v38, v90
	v_lshl_add_u64 v[104:105], v[42:43], 0, v[118:119]
	v_lshl_add_u64 v[106:107], v[42:43], 0, v[120:121]
	v_mfma_f32_32x32x16_bf16 v[16:31], v[78:81], v[82:85], v[16:31]
	v_lshl_add_u64 v[80:81], v[42:43], 0, v[108:109]
	v_lshl_add_u64 v[108:109], v[42:43], 0, v[122:123]
	v_or_b32_e32 v118, 0x4a, v34
	v_or_b32_e32 v122, 0x4b, v34
	v_ashrrev_i32_e32 v119, 31, v118
	v_ashrrev_i32_e32 v123, 31, v122
	v_lshlrev_b64 v[118:119], 10, v[118:119]
	v_mfma_f32_32x32x16_bf16 v[0:15], v[86:89], v[82:85], v[0:15]
	v_lshl_add_u64 v[82:83], v[42:43], 0, v[110:111]
	v_lshl_add_u64 v[84:85], v[42:43], 0, v[112:113]
	v_lshl_add_u64 v[86:87], v[42:43], 0, v[114:115]
	v_lshl_add_u64 v[88:89], v[42:43], 0, v[116:117]
	global_load_dword v90, v[80:81], off nt
	global_load_dword v130, v[82:83], off nt
	global_load_dword v143, v[84:85], off nt
	global_load_dword v146, v[86:87], off nt
	global_load_dword v147, v[88:89], off nt
	global_load_dword v148, v[104:105], off nt
	global_load_dword v149, v[106:107], off nt
	global_load_dword v150, v[108:109], off nt
	v_or_b32_e32 v80, 64, v34
	v_ashrrev_i32_e32 v81, 31, v80
	v_or_b32_e32 v84, 0x41, v34
	v_or_b32_e32 v88, 0x42, v34
	v_or_b32_e32 v106, 0x43, v34
	v_or_b32_e32 v110, 0x48, v34
	v_or_b32_e32 v114, 0x49, v34
	v_lshlrev_b64 v[80:81], 10, v[80:81]
	v_ashrrev_i32_e32 v85, 31, v84
	v_ashrrev_i32_e32 v89, 31, v88
	v_ashrrev_i32_e32 v107, 31, v106
	v_ashrrev_i32_e32 v111, 31, v110
	v_ashrrev_i32_e32 v115, 31, v114
	v_lshl_add_u64 v[82:83], v[40:41], 0, v[80:81]
	v_lshlrev_b64 v[84:85], 10, v[84:85]
	v_lshlrev_b64 v[88:89], 10, v[88:89]
	v_lshlrev_b64 v[106:107], 10, v[106:107]
	v_lshlrev_b64 v[110:111], 10, v[110:111]
	v_lshlrev_b64 v[114:115], 10, v[114:115]
	v_lshlrev_b64 v[122:123], 10, v[122:123]
	v_lshl_add_u64 v[86:87], v[40:41], 0, v[84:85]
	v_lshl_add_u64 v[104:105], v[40:41], 0, v[88:89]
	v_lshl_add_u64 v[108:109], v[40:41], 0, v[106:107]
	v_lshl_add_u64 v[112:113], v[40:41], 0, v[110:111]
	v_lshl_add_u64 v[116:117], v[40:41], 0, v[114:115]
	v_lshl_add_u64 v[120:121], v[40:41], 0, v[118:119]
	v_lshl_add_u64 v[144:145], v[40:41], 0, v[122:123]
	global_load_dword v151, v[82:83], off nt
	global_load_dword v152, v[86:87], off nt
	global_load_dword v153, v[104:105], off nt
	global_load_dword v182, v[108:109], off nt
	global_load_dword v183, v[112:113], off nt
	global_load_dword v184, v[116:117], off nt
	global_load_dword v185, v[120:121], off nt
	global_load_dword v186, v[144:145], off nt
	v_lshl_add_u64 v[80:81], v[42:43], 0, v[80:81]
	v_lshl_add_u64 v[82:83], v[42:43], 0, v[84:85]
	v_lshl_add_u64 v[84:85], v[42:43], 0, v[88:89]
	v_lshl_add_u64 v[86:87], v[42:43], 0, v[106:107]
	v_lshl_add_u64 v[88:89], v[42:43], 0, v[110:111]
	v_lshl_add_u64 v[104:105], v[42:43], 0, v[114:115]
	v_lshl_add_u64 v[106:107], v[42:43], 0, v[118:119]
	v_lshl_add_u64 v[108:109], v[42:43], 0, v[122:123]
	global_load_dword v187, v[80:81], off nt
	global_load_dword v188, v[82:83], off nt
	global_load_dword v189, v[84:85], off nt
	global_load_dword v190, v[86:87], off nt
	global_load_dword v191, v[88:89], off nt
	global_load_dword v192, v[104:105], off nt
	global_load_dword v193, v[106:107], off nt
	global_load_dword v194, v[108:109], off nt
	v_or_b32_e32 v80, 0x50, v34
	v_ashrrev_i32_e32 v81, 31, v80
	v_or_b32_e32 v84, 0x51, v34
	v_or_b32_e32 v88, 0x52, v34
	v_or_b32_e32 v106, 0x53, v34
	v_or_b32_e32 v110, 0x58, v34
	v_or_b32_e32 v114, 0x59, v34
	v_or_b32_e32 v118, 0x5a, v34
	v_or_b32_e32 v122, 0x5b, v34
	v_lshlrev_b64 v[80:81], 10, v[80:81]
	v_ashrrev_i32_e32 v85, 31, v84
	v_ashrrev_i32_e32 v89, 31, v88
	v_ashrrev_i32_e32 v107, 31, v106
	v_ashrrev_i32_e32 v111, 31, v110
	v_ashrrev_i32_e32 v115, 31, v114
	v_ashrrev_i32_e32 v119, 31, v118
	v_ashrrev_i32_e32 v123, 31, v122
	v_lshl_add_u64 v[82:83], v[40:41], 0, v[80:81]
	v_lshlrev_b64 v[84:85], 10, v[84:85]
	v_lshlrev_b64 v[88:89], 10, v[88:89]
	v_lshlrev_b64 v[106:107], 10, v[106:107]
	v_lshlrev_b64 v[110:111], 10, v[110:111]
	v_lshlrev_b64 v[114:115], 10, v[114:115]
	v_lshlrev_b64 v[118:119], 10, v[118:119]
	v_lshlrev_b64 v[122:123], 10, v[122:123]
	v_lshl_add_u64 v[86:87], v[40:41], 0, v[84:85]
	v_lshl_add_u64 v[104:105], v[40:41], 0, v[88:89]
	v_lshl_add_u64 v[108:109], v[40:41], 0, v[106:107]
	v_lshl_add_u64 v[112:113], v[40:41], 0, v[110:111]
	v_lshl_add_u64 v[116:117], v[40:41], 0, v[114:115]
	v_lshl_add_u64 v[120:121], v[40:41], 0, v[118:119]
	v_lshl_add_u64 v[144:145], v[40:41], 0, v[122:123]
	global_load_dword v195, v[82:83], off nt
	global_load_dword v196, v[86:87], off nt
	global_load_dword v197, v[104:105], off nt
	global_load_dword v198, v[108:109], off nt
	global_load_dword v199, v[112:113], off nt
	global_load_dword v200, v[116:117], off nt
	global_load_dword v201, v[120:121], off nt
	global_load_dword v202, v[144:145], off nt
	v_lshl_add_u64 v[80:81], v[42:43], 0, v[80:81]
	v_lshl_add_u64 v[82:83], v[42:43], 0, v[84:85]
	v_lshl_add_u64 v[84:85], v[42:43], 0, v[88:89]
	v_lshl_add_u64 v[86:87], v[42:43], 0, v[106:107]
	v_lshl_add_u64 v[88:89], v[42:43], 0, v[110:111]
	v_lshl_add_u64 v[104:105], v[42:43], 0, v[114:115]
	v_lshl_add_u64 v[106:107], v[42:43], 0, v[118:119]
	v_lshl_add_u64 v[108:109], v[42:43], 0, v[122:123]
	global_load_dword v203, v[80:81], off nt
	global_load_dword v204, v[82:83], off nt
	global_load_dword v205, v[84:85], off nt
	global_load_dword v206, v[86:87], off nt
	global_load_dword v207, v[88:89], off nt
	global_load_dword v208, v[104:105], off nt
	global_load_dword v209, v[106:107], off nt
	global_load_dword v221, v[108:109], off nt
	v_or_b32_e32 v80, 0x60, v34
	v_or_b32_e32 v122, 0x6b, v34
	v_ashrrev_i32_e32 v81, 31, v80
	v_or_b32_e32 v84, 0x61, v34
	v_or_b32_e32 v88, 0x62, v34
	v_or_b32_e32 v106, 0x63, v34
	v_or_b32_e32 v110, 0x68, v34
	v_or_b32_e32 v114, 0x69, v34
	v_or_b32_e32 v118, 0x6a, v34
	v_ashrrev_i32_e32 v123, 31, v122
	v_fma_f32 v77, v77, s18, -v181
	v_lshlrev_b64 v[80:81], 10, v[80:81]
	v_ashrrev_i32_e32 v85, 31, v84
	v_ashrrev_i32_e32 v89, 31, v88
	v_ashrrev_i32_e32 v107, 31, v106
	v_ashrrev_i32_e32 v111, 31, v110
	v_ashrrev_i32_e32 v115, 31, v114
	v_ashrrev_i32_e32 v119, 31, v118
	v_lshlrev_b64 v[122:123], 10, v[122:123]
	v_exp_f32_e32 v77, v77
	v_fma_f32 v76, v76, s18, -v181
	v_lshl_add_u64 v[82:83], v[40:41], 0, v[80:81]
	v_lshlrev_b64 v[84:85], 10, v[84:85]
	v_lshlrev_b64 v[88:89], 10, v[88:89]
	v_lshlrev_b64 v[106:107], 10, v[106:107]
	v_lshlrev_b64 v[110:111], 10, v[110:111]
	v_lshlrev_b64 v[114:115], 10, v[114:115]
	v_lshlrev_b64 v[118:119], 10, v[118:119]
	v_lshl_add_u64 v[144:145], v[40:41], 0, v[122:123]
	v_exp_f32_e32 v76, v76
	s_waitcnt vmcnt(46)
	v_cvt_pk_bf16_f32 v36, v228, v229
	v_lshl_add_u64 v[86:87], v[40:41], 0, v[84:85]
	v_lshl_add_u64 v[104:105], v[40:41], 0, v[88:89]
	v_lshl_add_u64 v[108:109], v[40:41], 0, v[106:107]
	v_lshl_add_u64 v[112:113], v[40:41], 0, v[110:111]
	v_lshl_add_u64 v[116:117], v[40:41], 0, v[114:115]
	v_lshl_add_u64 v[120:121], v[40:41], 0, v[118:119]
	global_load_dword v222, v[82:83], off nt
	global_load_dword v223, v[86:87], off nt
	global_load_dword v224, v[104:105], off nt
	global_load_dword v225, v[108:109], off nt
	global_load_dword v226, v[112:113], off nt
	global_load_dword v227, v[116:117], off nt
	global_load_dword v228, v[120:121], off nt
	s_nop 0
	global_load_dword v144, v[144:145], off nt
	v_add_f32_e32 v32, v77, v35
	v_add_f32_e32 v79, v76, v32
	v_fma_f32 v32, s17, v180, -v181
	v_lshl_add_u64 v[80:81], v[42:43], 0, v[80:81]
	v_exp_f32_e32 v78, v32
	v_cvt_pk_bf16_f32 v32, v37, v39
	s_waitcnt vmcnt(52)
	v_cvt_pk_bf16_f32 v37, v230, v231
	s_waitcnt vmcnt(50)
	v_cvt_pk_bf16_f32 v38, v232, v233
	v_lshl_add_u64 v[82:83], v[42:43], 0, v[84:85]
	v_lshl_add_u64 v[84:85], v[42:43], 0, v[88:89]
	v_lshl_add_u64 v[86:87], v[42:43], 0, v[106:107]
	v_lshl_add_u64 v[88:89], v[42:43], 0, v[110:111]
	v_lshl_add_u64 v[104:105], v[42:43], 0, v[114:115]
	v_lshl_add_u64 v[106:107], v[42:43], 0, v[118:119]
	v_lshl_add_u64 v[108:109], v[42:43], 0, v[122:123]
	global_load_dword v122, v[80:81], off nt
	global_load_dword v123, v[82:83], off nt
	global_load_dword v145, v[84:85], off nt
	global_load_dword v229, v[86:87], off nt
	global_load_dword v230, v[88:89], off nt
	global_load_dword v231, v[104:105], off nt
	global_load_dword v232, v[106:107], off nt
	global_load_dword v233, v[108:109], off nt
	v_or_b32_e32 v80, 0x70, v34
	v_or_b32_e32 v106, 0x73, v34
	v_or_b32_e32 v110, 0x78, v34
	v_or_b32_e32 v114, 0x79, v34
	v_ashrrev_i32_e32 v81, 31, v80
	v_or_b32_e32 v84, 0x71, v34
	v_or_b32_e32 v88, 0x72, v34
	v_ashrrev_i32_e32 v107, 31, v106
	v_ashrrev_i32_e32 v111, 31, v110
	v_ashrrev_i32_e32 v115, 31, v114
	v_or_b32_e32 v118, 0x7a, v34
	v_or_b32_e32 v34, 0x7b, v34
	v_lshlrev_b64 v[80:81], 10, v[80:81]
	v_ashrrev_i32_e32 v85, 31, v84
	v_ashrrev_i32_e32 v89, 31, v88
	v_lshlrev_b64 v[106:107], 10, v[106:107]
	v_lshlrev_b64 v[110:111], 10, v[110:111]
	v_lshlrev_b64 v[114:115], 10, v[114:115]
	v_ashrrev_i32_e32 v119, 31, v118
	v_ashrrev_i32_e32 v35, 31, v34
	v_lshl_add_u64 v[82:83], v[40:41], 0, v[80:81]
	v_lshlrev_b64 v[84:85], 10, v[84:85]
	v_lshlrev_b64 v[88:89], 10, v[88:89]
	v_lshl_add_u64 v[108:109], v[40:41], 0, v[106:107]
	v_lshl_add_u64 v[112:113], v[40:41], 0, v[110:111]
	v_lshl_add_u64 v[116:117], v[40:41], 0, v[114:115]
	v_lshlrev_b64 v[118:119], 10, v[118:119]
	v_lshlrev_b64 v[34:35], 10, v[34:35]
	s_waitcnt vmcnt(56)
	v_cvt_pk_bf16_f32 v39, v234, v235
	v_lshl_add_u64 v[86:87], v[40:41], 0, v[84:85]
	v_lshl_add_u64 v[104:105], v[40:41], 0, v[88:89]
	v_lshl_add_u64 v[120:121], v[40:41], 0, v[118:119]
	v_lshl_add_u64 v[40:41], v[40:41], 0, v[34:35]
	global_load_dword v234, v[82:83], off nt
	global_load_dword v235, v[86:87], off nt
	global_load_dword v236, v[104:105], off nt
	s_nop 0
	global_load_dword v108, v[108:109], off nt
	s_nop 0
	global_load_dword v109, v[112:113], off nt
	s_nop 0
	global_load_dword v112, v[116:117], off nt
	global_load_dword v113, v[120:121], off nt
	s_nop 0
	global_load_dword v116, v[40:41], off nt
	v_lshl_add_u64 v[40:41], v[42:43], 0, v[80:81]
	v_lshl_add_u64 v[80:81], v[42:43], 0, v[84:85]
	v_lshl_add_u64 v[82:83], v[42:43], 0, v[88:89]
	v_lshl_add_u64 v[84:85], v[42:43], 0, v[106:107]
	v_lshl_add_u64 v[86:87], v[42:43], 0, v[110:111]
	v_lshl_add_u64 v[88:89], v[42:43], 0, v[114:115]
	v_lshl_add_u64 v[104:105], v[42:43], 0, v[118:119]
	v_lshl_add_u64 v[34:35], v[42:43], 0, v[34:35]
	global_load_dword v40, v[40:41], off nt
	s_nop 0
	global_load_dword v41, v[80:81], off nt
	global_load_dword v42, v[82:83], off nt
	global_load_dword v43, v[84:85], off nt
	s_nop 0
	global_load_dword v80, v[86:87], off nt
	global_load_dword v81, v[88:89], off nt
	global_load_dword v82, v[104:105], off nt
	global_load_dword v83, v[34:35], off nt
	v_cvt_pk_bf16_f32 v33, v33, v64
	v_cvt_pk_bf16_f32 v34, v65, v66
	v_cvt_pk_bf16_f32 v35, v67, v69
	v_add_f32_e32 v64, v78, v79
	v_add_f32_e32 v64, v78, v64
	v_mfma_f32_32x32x16_bf16 v[16:31], v[36:39], v[32:35], v[16:31]
	s_waitcnt vmcnt(62)
	v_cvt_pk_bf16_f32 v36, v90, v130
	v_cvt_pk_bf16_f32 v37, v143, v146
	v_cvt_pk_bf16_f32 v38, v147, v148
	v_cvt_pk_bf16_f32 v39, v149, v150
	v_add_f32_e32 v64, v78, v64
	v_add_f32_e32 v64, v78, v64
	s_ashr_i32 s95, s94, 31
	v_mfma_f32_32x32x16_bf16 v[0:15], v[36:39], v[32:35], v[0:15]
	v_cvt_pk_bf16_f32 v32, v151, v152
	s_waitcnt vmcnt(60)
	v_cvt_pk_bf16_f32 v33, v153, v182
	s_waitcnt vmcnt(58)
	v_cvt_pk_bf16_f32 v34, v183, v184
	s_waitcnt vmcnt(56)
	v_cvt_pk_bf16_f32 v35, v185, v186
	v_cvt_pk_bf16_f32 v36, v44, v45
	v_cvt_pk_bf16_f32 v37, v46, v47
	v_cvt_pk_bf16_f32 v38, v49, v51
	v_cvt_pk_bf16_f32 v39, v53, v55
	v_add_f32_e32 v44, v78, v64
	v_add_f32_e32 v44, v78, v44
	v_mfma_f32_32x32x16_bf16 v[16:31], v[32:35], v[36:39], v[16:31]
	s_waitcnt vmcnt(54)
	v_cvt_pk_bf16_f32 v32, v187, v188
	s_waitcnt vmcnt(52)
	v_cvt_pk_bf16_f32 v33, v189, v190
	s_waitcnt vmcnt(50)
	v_cvt_pk_bf16_f32 v34, v191, v192
	s_waitcnt vmcnt(48)
	v_cvt_pk_bf16_f32 v35, v193, v194
	v_add_f32_e32 v44, v78, v44
	v_add_f32_e32 v44, v78, v44
	v_add_f32_e32 v44, v78, v44
	v_mfma_f32_32x32x16_bf16 v[0:15], v[32:35], v[36:39], v[0:15]
	s_waitcnt vmcnt(46)
	v_cvt_pk_bf16_f32 v32, v195, v196
	s_waitcnt vmcnt(44)
	v_cvt_pk_bf16_f32 v33, v197, v198
	s_waitcnt vmcnt(42)
	v_cvt_pk_bf16_f32 v34, v199, v200
	s_waitcnt vmcnt(40)
	v_cvt_pk_bf16_f32 v35, v201, v202
	v_cvt_pk_bf16_f32 v36, v48, v50
	v_cvt_pk_bf16_f32 v37, v52, v54
	v_cvt_pk_bf16_f32 v38, v57, v59
	v_cvt_pk_bf16_f32 v39, v61, v70
	v_add_f32_e32 v44, v78, v44
	v_add_f32_e32 v44, v78, v44
	v_mfma_f32_32x32x16_bf16 v[16:31], v[32:35], v[36:39], v[16:31]
	s_waitcnt vmcnt(38)
	v_cvt_pk_bf16_f32 v32, v203, v204
	s_waitcnt vmcnt(36)
	v_cvt_pk_bf16_f32 v33, v205, v206
	s_waitcnt vmcnt(34)
	v_cvt_pk_bf16_f32 v34, v207, v208
	s_waitcnt vmcnt(32)
	v_cvt_pk_bf16_f32 v35, v209, v221
	v_add_f32_e32 v183, v78, v44
	ds_bpermute_b32 v184, v68, v183
	s_lshl_b64 s[24:25], s[94:95], 9
	v_mfma_f32_32x32x16_bf16 v[0:15], v[32:35], v[36:39], v[0:15]
	s_waitcnt vmcnt(30)
	v_cvt_pk_bf16_f32 v32, v222, v223
	s_waitcnt vmcnt(28)
	v_cvt_pk_bf16_f32 v33, v224, v225
	s_waitcnt vmcnt(26)
	v_cvt_pk_bf16_f32 v34, v226, v227
	s_waitcnt vmcnt(24)
	v_cvt_pk_bf16_f32 v35, v228, v144
	v_cvt_pk_bf16_f32 v36, v56, v58
	v_cvt_pk_bf16_f32 v37, v60, v63
	v_cvt_pk_bf16_f32 v38, v71, v73
	v_cvt_pk_bf16_f32 v39, v74, v75
	s_add_u32 s13, s56, s24
	s_addc_u32 s15, s57, s25
	v_mfma_f32_32x32x16_bf16 v[16:31], v[32:35], v[36:39], v[16:31]
	s_waitcnt vmcnt(22)
	v_cvt_pk_bf16_f32 v32, v122, v123
	s_waitcnt vmcnt(20)
	v_cvt_pk_bf16_f32 v33, v145, v229
	s_waitcnt vmcnt(18)
	v_cvt_pk_bf16_f32 v34, v230, v231
	s_waitcnt vmcnt(16)
	v_cvt_pk_bf16_f32 v35, v232, v233
	s_lshl_b32 s14, s14, 1
	s_add_u32 s94, s13, s14
	s_addc_u32 s95, s15, 0
	v_mfma_f32_32x32x16_bf16 v[0:15], v[32:35], v[36:39], v[0:15]
	s_waitcnt vmcnt(14)
	v_cvt_pk_bf16_f32 v32, v234, v235
	s_waitcnt vmcnt(12)
	v_cvt_pk_bf16_f32 v33, v236, v108
	s_waitcnt vmcnt(10)
	v_cvt_pk_bf16_f32 v34, v109, v112
	s_waitcnt vmcnt(8)
	v_cvt_pk_bf16_f32 v35, v113, v116
	v_cvt_pk_bf16_f32 v36, v62, v72
	v_cvt_pk_bf16_f32 v37, v93, v94
	v_cvt_pk_bf16_f32 v38, v95, v98
	v_cvt_pk_bf16_f32 v39, v99, v102
	v_readlane_b32 s69, v254, 19
	v_readlane_b32 s70, v254, 20
	v_mfma_f32_32x32x16_bf16 v[16:31], v[32:35], v[36:39], v[16:31]
	s_waitcnt vmcnt(6)
	v_cvt_pk_bf16_f32 v32, v40, v41
	s_waitcnt vmcnt(4)
	v_cvt_pk_bf16_f32 v33, v42, v43
	s_waitcnt vmcnt(2)
	v_cvt_pk_bf16_f32 v34, v80, v81
	s_waitcnt vmcnt(0)
	v_cvt_pk_bf16_f32 v35, v82, v83
	v_readlane_b32 s71, v254, 21
	s_nop 0
	v_mfma_f32_32x32x16_bf16 v[0:15], v[32:35], v[36:39], v[0:15]
	v_mov_b32_e32 v34, 0
	v_mov_b32_e32 v32, 0
	v_mov_b32_e32 v33, 0
	s_and_saveexec_b64 vcc, s[4:5]
	s_cbranch_execz .LBB0_742
	v_lshlrev_b32_e32 v33, 1, v136
	global_load_ushort v32, v33, s[94:95]
	global_load_ushort v35, v33, s[94:95] offset:512
	s_waitcnt vmcnt(0)
	v_lshl_or_b32 v32, v35, 16, v32
	global_load_ushort v35, v33, s[94:95] offset:1024
	s_nop 0
	global_load_ushort v33, v33, s[94:95] offset:1536
	s_waitcnt vmcnt(0)
	v_lshl_or_b32 v33, v33, 16, v35

.LBB0_1005:
	s_or_b64 exec, exec, s[4:5]
	v_readlane_b32 s2, v254, 0
	s_nop 0
	s_cmpk_lt_u32 s2, 64
	s_cselect_b32 s6, 0x100, 0
	s_xor_b32 s2, s2, s6
	s_cmpk_lt_i32 s2, 0x140
	s_cselect_b64 s[4:5], -1, 0
	s_cmpk_gt_i32 s2, 0x13f
	v_readfirstlane_b32 s33, v171
	s_waitcnt lgkmcnt(0)
	s_barrier
	s_cbranch_scc1 .LBB0_1008
	s_cmpk_lt_i32 s2, 0x100
	s_cselect_b64 s[6:7], -1, 0
	s_and_b64 s[6:7], s[6:7], exec
	s_cselect_b32 s6, s2, 0
	s_ashr_i32 s7, s6, 31
	s_lshr_b32 s7, s7, 29
	s_add_i32 s10, s6, s7
	s_and_b32 s7, s10, -8
	s_sub_i32 s8, s6, s7
	s_cmp_gt_i32 s8, -1
	s_cbranch_scc0 .LBB0_1009
	s_lshl_b32 s9, s8, 5
	s_ashr_i32 s6, s10, 3
	s_cbranch_execz .LBB0_1010
	s_branch .LBB0_1011

.LBB0_1011:
	s_add_i32 s6, s9, s6
	s_ashr_i32 s7, s6, 31
	s_lshr_b32 s7, s7, 26
	s_add_i32 s7, s6, s7
	s_ashr_i32 s8, s7, 6
	s_and_b32 s7, s7, 0xffc0
	s_sub_i32 s6, s6, s7
	s_bfe_i32 s7, s6, 0x80000
	s_bfe_u32 s7, s7, 0x3000c
	s_add_i32 s7, s6, s7
	s_bfe_i32 s9, s7, 0x80000
	s_and_b32 s7, s7, 0xf8
	s_sub_i32 s6, s6, s7
	s_lshl_b32 s8, s8, 3
	s_sext_i32_i8 s6, s6
	v_readlane_b32 s2, v254, 0
	s_nop 0
	s_cmpk_lt_u32 s2, 64
	s_cselect_b32 s12, 0x100, 0
	s_xor_b32 s2, s2, s12
	s_add_i32 s8, s8, s6
	s_add_i32 s6, s2, 0xffffff00
	s_sext_i32_i16 s9, s9
	s_lshr_b32 s6, s6, 5
	s_nop 0
	s_ashr_i32 s9, s9, 3
	s_add_i32 s10, s6, 32
	s_cmpk_lt_i32 s2, 0x100
	s_cselect_b64 s[12:13], -1, 0
	s_and_b64 s[6:7], s[12:13], exec
	s_cselect_b32 s34, s8, s10
	s_bfe_u32 s8, s2, 0x30002
	s_and_b64 s[6:7], s[12:13], exec
	s_cselect_b32 s30, s9, s8
	s_cselect_b32 s17, 32, 8
	s_and_b32 s8, s2, 3
	s_lshl_b32 s9, s8, 10
	s_and_b64 s[6:7], s[12:13], exec
	s_cselect_b32 s12, -1, s8
	s_mov_b32 s15, 0
	s_cselect_b32 s14, 0, s9

.LBB0_1017:
	s_add_i32 s55, s55, 1
	s_mul_i32 s23, s55, s76
	v_readlane_b32 s2, v254, 0
	s_add_i32 s23, s23, s2
	s_cmpk_lt_u32 s2, 64
	s_cselect_b32 s38, 0x100, 0
	s_xor_b32 s23, s23, s38
	s_cmpk_lt_i32 s23, 0x140
	s_cselect_b64 s[38:39], -1, 0
	s_cmpk_gt_i32 s23, 0x13f
	s_cselect_b64 s[18:19], -1, 0
	s_and_b64 vcc, exec, s[18:19]
	s_cbranch_vccnz .LBB0_1023
	s_cmpk_lt_i32 s23, 0x100
	s_cselect_b64 s[24:25], -1, 0
	s_and_b64 s[20:21], s[24:25], exec
	s_cselect_b32 s20, s23, 0
	s_ashr_i32 s21, s20, 31
	s_lshr_b32 s21, s21, 29
	s_add_i32 s22, s20, s21
	s_and_b32 s21, s22, -8
	s_sub_i32 s26, s20, s21
	s_cmp_gt_i32 s26, -1
	s_mov_b64 s[20:21], -1
	s_cbranch_scc0 .LBB0_1020
	s_lshl_b32 s27, s26, 5
	s_mov_b64 s[20:21], 0

.LBB0_1024:
	s_waitcnt lgkmcnt(0)
	ds_read_b128 v[128:131], v179
	ds_read_b128 v[132:135], v179 offset:1024
	ds_read_b128 v[136:139], v179 offset:2048
	ds_read_b128 v[140:143], v179 offset:3072
	s_add_i32 s62, s36, 2
	s_add_u32 s37, s4, 0xfff80080
	s_addc_u32 s38, s5, -1
	s_cmp_eq_u32 s59, s36
	s_cselect_b32 s36, s58, s60
	s_cselect_b32 s39, s21, s38
	s_cselect_b32 s38, s25, s37
	s_cselect_b32 s37, s23, s61
	v_lshl_add_u64 v[166:167], s[4:5], 0, v[162:163]
	s_add_i32 m0, s31, 0xc000
	ds_read_b128 v[144:147], v190
	ds_read_b128 v[148:151], v190 offset:1024
	ds_read_b128 v[152:155], v190 offset:2048
	ds_read_b128 v[156:159], v190 offset:3072
	ds_read_b128 v[180:183], v190 offset:4096
	ds_read_b128 v[184:187], v190 offset:5120
	ds_read_b128 v[194:197], v190 offset:6144
	ds_read_b128 v[198:201], v190 offset:7168
	global_load_lds_dwordx4 v[166:167], off
	v_lshl_add_u64 v[166:167], s[4:5], 0, v[164:165]
	s_add_i32 m0, s31, 0xe000
	s_nop 0
	global_load_lds_dwordx4 v[166:167], off
	s_waitcnt lgkmcnt(8)
	s_barrier
	s_waitcnt lgkmcnt(0)
	s_setprio 1
	s_waitcnt lgkmcnt(0)
	v_mfma_f32_16x16x32_bf16 v[124:127], v[128:131], v[144:147], v[124:127]
	v_mfma_f32_16x16x32_bf16 v[120:123], v[136:139], v[144:147], v[120:123]
	v_mfma_f32_16x16x32_bf16 v[116:119], v[128:131], v[152:155], v[116:119]
	v_mfma_f32_16x16x32_bf16 v[104:107], v[136:139], v[152:155], v[104:107]
	v_mfma_f32_16x16x32_bf16 v[96:99], v[128:131], v[180:183], v[96:99]
	v_mfma_f32_16x16x32_bf16 v[88:91], v[136:139], v[180:183], v[88:91]
	v_mfma_f32_16x16x32_bf16 v[80:83], v[128:131], v[194:197], v[80:83]
	v_mfma_f32_16x16x32_bf16 v[72:75], v[136:139], v[194:197], v[72:75]
	v_mfma_f32_16x16x32_bf16 v[124:127], v[132:135], v[148:151], v[124:127]
	v_mfma_f32_16x16x32_bf16 v[120:123], v[140:143], v[148:151], v[120:123]
	v_mfma_f32_16x16x32_bf16 v[116:119], v[132:135], v[156:159], v[116:119]
	v_mfma_f32_16x16x32_bf16 v[104:107], v[140:143], v[156:159], v[104:107]
	v_mfma_f32_16x16x32_bf16 v[96:99], v[132:135], v[184:187], v[96:99]
	v_mfma_f32_16x16x32_bf16 v[88:91], v[140:143], v[184:187], v[88:91]
	v_mfma_f32_16x16x32_bf16 v[80:83], v[132:135], v[198:201], v[80:83]
	v_mfma_f32_16x16x32_bf16 v[72:75], v[140:143], v[198:201], v[72:75]
	s_setprio 0
	s_barrier
	s_add_i32 s63, s52, s42
	v_lshl_add_u64 v[166:167], s[36:37], 0, v[172:173]
	s_mov_b32 m0, s63
	ds_read_b128 v[202:205], v191
	ds_read_b128 v[206:209], v191 offset:1024
	ds_read_b128 v[222:225], v191 offset:2048
	ds_read_b128 v[226:229], v191 offset:3072
	global_load_lds_dwordx4 v[166:167], off
	v_lshl_add_u64 v[188:189], s[36:37], 0, v[174:175]
	s_add_i32 m0, s63, 0x2000
	s_nop 0
	global_load_lds_dwordx4 v[188:189], off
	s_barrier
	s_waitcnt lgkmcnt(0)
	s_setprio 1
	s_waitcnt lgkmcnt(0)
	v_mfma_f32_16x16x32_bf16 v[112:115], v[202:205], v[144:147], v[112:115]
	v_mfma_f32_16x16x32_bf16 v[108:111], v[222:225], v[144:147], v[108:111]
	v_mfma_f32_16x16x32_bf16 v[100:103], v[202:205], v[152:155], v[100:103]
	v_mfma_f32_16x16x32_bf16 v[92:95], v[222:225], v[152:155], v[92:95]
	v_mfma_f32_16x16x32_bf16 v[84:87], v[202:205], v[180:183], v[84:87]
	v_mfma_f32_16x16x32_bf16 v[76:79], v[222:225], v[180:183], v[76:79]
	v_mfma_f32_16x16x32_bf16 v[68:71], v[202:205], v[194:197], v[68:71]
	v_mfma_f32_16x16x32_bf16 v[64:67], v[222:225], v[194:197], v[64:67]
	v_mfma_f32_16x16x32_bf16 v[112:115], v[206:209], v[148:151], v[112:115]
	v_mfma_f32_16x16x32_bf16 v[108:111], v[226:229], v[148:151], v[108:111]
	v_mfma_f32_16x16x32_bf16 v[100:103], v[206:209], v[156:159], v[100:103]
	v_mfma_f32_16x16x32_bf16 v[92:95], v[226:229], v[156:159], v[92:95]
	v_mfma_f32_16x16x32_bf16 v[84:87], v[206:209], v[184:187], v[84:87]
	v_mfma_f32_16x16x32_bf16 v[76:79], v[226:229], v[184:187], v[76:79]
	v_mfma_f32_16x16x32_bf16 v[68:71], v[206:209], v[198:201], v[68:71]
	v_mfma_f32_16x16x32_bf16 v[64:67], v[226:229], v[198:201], v[64:67]
	s_setprio 0
	s_mov_b32 m0, s31
	v_lshl_add_u64 v[230:231], s[38:39], 0, v[172:173]
	s_barrier
	ds_read_b128 v[144:147], v190 offset:16384
	ds_read_b128 v[148:151], v190 offset:17408
	ds_read_b128 v[152:155], v190 offset:18432
	ds_read_b128 v[156:159], v190 offset:19456
	ds_read_b128 v[180:183], v190 offset:20480
	ds_read_b128 v[184:187], v190 offset:21504
	ds_read_b128 v[194:197], v190 offset:22528
	ds_read_b128 v[198:201], v190 offset:23552
	global_load_lds_dwordx4 v[230:231], off
	v_lshl_add_u64 v[232:233], s[38:39], 0, v[174:175]
	s_mov_b32 m0, s35
	s_nop 0
	global_load_lds_dwordx4 v[232:233], off
	s_barrier
	s_waitcnt lgkmcnt(0)
	s_setprio 1
	s_waitcnt lgkmcnt(0)
	v_mfma_f32_16x16x32_bf16 v[60:63], v[128:131], v[144:147], v[60:63]
	v_mfma_f32_16x16x32_bf16 v[56:59], v[136:139], v[144:147], v[56:59]
	v_mfma_f32_16x16x32_bf16 v[52:55], v[128:131], v[152:155], v[52:55]
	v_mfma_f32_16x16x32_bf16 v[40:43], v[136:139], v[152:155], v[40:43]
	v_mfma_f32_16x16x32_bf16 v[36:39], v[128:131], v[180:183], v[36:39]
	v_mfma_f32_16x16x32_bf16 v[24:27], v[136:139], v[180:183], v[24:27]
	v_mfma_f32_16x16x32_bf16 v[20:23], v[128:131], v[194:197], v[20:23]
	v_mfma_f32_16x16x32_bf16 v[8:11], v[136:139], v[194:197], v[8:11]
	v_mfma_f32_16x16x32_bf16 v[60:63], v[132:135], v[148:151], v[60:63]
	v_mfma_f32_16x16x32_bf16 v[56:59], v[140:143], v[148:151], v[56:59]
	v_mfma_f32_16x16x32_bf16 v[52:55], v[132:135], v[156:159], v[52:55]
	v_mfma_f32_16x16x32_bf16 v[40:43], v[140:143], v[156:159], v[40:43]
	v_mfma_f32_16x16x32_bf16 v[36:39], v[132:135], v[184:187], v[36:39]
	v_mfma_f32_16x16x32_bf16 v[24:27], v[140:143], v[184:187], v[24:27]
	v_mfma_f32_16x16x32_bf16 v[20:23], v[132:135], v[198:201], v[20:23]
	v_mfma_f32_16x16x32_bf16 v[8:11], v[140:143], v[198:201], v[8:11]
	s_setprio 0
	s_barrier
	s_add_u32 s64, s36, 0x80000
	s_addc_u32 s65, s37, 0
	s_add_i32 s63, s53, s42
	v_lshl_add_u64 v[128:129], s[64:65], 0, v[172:173]
	s_mov_b32 m0, s63
	s_nop 0
	global_load_lds_dwordx4 v[128:129], off
	v_lshl_add_u64 v[128:129], s[64:65], 0, v[174:175]
	s_add_i32 m0, s63, 0x2000
	s_nop 0
	global_load_lds_dwordx4 v[128:129], off
	s_waitcnt vmcnt(6)
	s_barrier
	s_setprio 1
	v_mfma_f32_16x16x32_bf16 v[48:51], v[202:205], v[144:147], v[48:51]
	v_mfma_f32_16x16x32_bf16 v[44:47], v[222:225], v[144:147], v[44:47]
	v_mfma_f32_16x16x32_bf16 v[32:35], v[202:205], v[152:155], v[32:35]
	v_mfma_f32_16x16x32_bf16 v[28:31], v[222:225], v[152:155], v[28:31]
	v_mfma_f32_16x16x32_bf16 v[16:19], v[202:205], v[180:183], v[16:19]
	v_mfma_f32_16x16x32_bf16 v[12:15], v[222:225], v[180:183], v[12:15]
	v_mfma_f32_16x16x32_bf16 v[4:7], v[202:205], v[194:197], v[4:7]
	v_mfma_f32_16x16x32_bf16 v[0:3], v[222:225], v[194:197], v[0:3]
	v_mfma_f32_16x16x32_bf16 v[48:51], v[206:209], v[148:151], v[48:51]
	v_mfma_f32_16x16x32_bf16 v[44:47], v[226:229], v[148:151], v[44:47]
	v_mfma_f32_16x16x32_bf16 v[32:35], v[206:209], v[156:159], v[32:35]
	v_mfma_f32_16x16x32_bf16 v[28:31], v[226:229], v[156:159], v[28:31]
	v_mfma_f32_16x16x32_bf16 v[16:19], v[206:209], v[184:187], v[16:19]
	v_mfma_f32_16x16x32_bf16 v[12:15], v[226:229], v[184:187], v[12:15]
	v_mfma_f32_16x16x32_bf16 v[4:7], v[206:209], v[198:201], v[4:7]
	v_mfma_f32_16x16x32_bf16 v[0:3], v[226:229], v[198:201], v[0:3]
	s_setprio 0
	s_add_i32 s63, 0, 0x18000
	v_add_u32_e32 v140, s63, v177
	s_barrier
	ds_read_b128 v[128:131], v140
	ds_read_b128 v[132:135], v140 offset:1024
	ds_read_b128 v[136:139], v140 offset:2048
	ds_read_b128 v[140:143], v140 offset:3072
	s_add_u32 s38, s38, 0x80000
	s_addc_u32 s39, s39, 0
	s_mov_b32 m0, s43
	v_lshl_add_u64 v[202:203], s[38:39], 0, v[172:173]
	ds_read_b128 v[144:147], v190 offset:32768
	ds_read_b128 v[148:151], v190 offset:33792
	ds_read_b128 v[152:155], v190 offset:34816
	ds_read_b128 v[156:159], v190 offset:35840
	ds_read_b128 v[180:183], v190 offset:36864
	ds_read_b128 v[184:187], v190 offset:37888
	ds_read_b128 v[194:197], v190 offset:38912
	ds_read_b128 v[198:201], v190 offset:39936
	global_load_lds_dwordx4 v[202:203], off
	v_lshl_add_u64 v[202:203], s[38:39], 0, v[174:175]
	s_mov_b32 m0, s44
	s_nop 0
	global_load_lds_dwordx4 v[202:203], off
	s_waitcnt lgkmcnt(8)
	s_barrier
	s_waitcnt lgkmcnt(0)
	s_setprio 1
	s_waitcnt lgkmcnt(0)
	v_mfma_f32_16x16x32_bf16 v[124:127], v[128:131], v[144:147], v[124:127]
	v_mfma_f32_16x16x32_bf16 v[120:123], v[136:139], v[144:147], v[120:123]
	v_mfma_f32_16x16x32_bf16 v[116:119], v[128:131], v[152:155], v[116:119]
	v_mfma_f32_16x16x32_bf16 v[104:107], v[136:139], v[152:155], v[104:107]
	v_mfma_f32_16x16x32_bf16 v[96:99], v[128:131], v[180:183], v[96:99]
	v_mfma_f32_16x16x32_bf16 v[88:91], v[136:139], v[180:183], v[88:91]
	v_mfma_f32_16x16x32_bf16 v[80:83], v[128:131], v[194:197], v[80:83]
	v_mfma_f32_16x16x32_bf16 v[72:75], v[136:139], v[194:197], v[72:75]
	v_mfma_f32_16x16x32_bf16 v[124:127], v[132:135], v[148:151], v[124:127]
	v_mfma_f32_16x16x32_bf16 v[120:123], v[140:143], v[148:151], v[120:123]
	v_mfma_f32_16x16x32_bf16 v[116:119], v[132:135], v[156:159], v[116:119]
	v_mfma_f32_16x16x32_bf16 v[104:107], v[140:143], v[156:159], v[104:107]
	v_mfma_f32_16x16x32_bf16 v[96:99], v[132:135], v[184:187], v[96:99]
	v_mfma_f32_16x16x32_bf16 v[88:91], v[140:143], v[184:187], v[88:91]
	v_mfma_f32_16x16x32_bf16 v[80:83], v[132:135], v[198:201], v[80:83]
	v_mfma_f32_16x16x32_bf16 v[72:75], v[140:143], v[198:201], v[72:75]
	s_setprio 0
	s_barrier
	s_add_i32 s38, 0, 0x1c000
	s_add_i32 s39, s63, s42
	v_add_u32_e32 v160, s38, v177
	v_lshl_add_u64 v[166:167], v[166:167], 0, s[14:15]
	s_mov_b32 m0, s39
	ds_read_b128 v[202:205], v160
	ds_read_b128 v[206:209], v160 offset:1024
	ds_read_b128 v[222:225], v160 offset:2048
	ds_read_b128 v[226:229], v160 offset:3072
	global_load_lds_dwordx4 v[166:167], off
	v_lshl_add_u64 v[166:167], v[188:189], 0, s[14:15]
	s_add_i32 m0, s39, 0x2000
	s_nop 0
	global_load_lds_dwordx4 v[166:167], off
	s_barrier
	s_waitcnt lgkmcnt(0)
	s_setprio 1
	s_waitcnt lgkmcnt(0)
	v_mfma_f32_16x16x32_bf16 v[112:115], v[202:205], v[144:147], v[112:115]
	v_mfma_f32_16x16x32_bf16 v[108:111], v[222:225], v[144:147], v[108:111]
	v_mfma_f32_16x16x32_bf16 v[100:103], v[202:205], v[152:155], v[100:103]
	v_mfma_f32_16x16x32_bf16 v[92:95], v[222:225], v[152:155], v[92:95]
	v_mfma_f32_16x16x32_bf16 v[84:87], v[202:205], v[180:183], v[84:87]
	v_mfma_f32_16x16x32_bf16 v[76:79], v[222:225], v[180:183], v[76:79]
	v_mfma_f32_16x16x32_bf16 v[68:71], v[202:205], v[194:197], v[68:71]
	v_mfma_f32_16x16x32_bf16 v[64:67], v[222:225], v[194:197], v[64:67]
	v_mfma_f32_16x16x32_bf16 v[112:115], v[206:209], v[148:151], v[112:115]
	v_mfma_f32_16x16x32_bf16 v[108:111], v[226:229], v[148:151], v[108:111]
	v_mfma_f32_16x16x32_bf16 v[100:103], v[206:209], v[156:159], v[100:103]
	v_mfma_f32_16x16x32_bf16 v[92:95], v[226:229], v[156:159], v[92:95]
	v_mfma_f32_16x16x32_bf16 v[84:87], v[206:209], v[184:187], v[84:87]
	v_mfma_f32_16x16x32_bf16 v[76:79], v[226:229], v[184:187], v[76:79]
	v_mfma_f32_16x16x32_bf16 v[68:71], v[206:209], v[198:201], v[68:71]
	v_mfma_f32_16x16x32_bf16 v[64:67], v[226:229], v[198:201], v[64:67]
	s_setprio 0
	s_mov_b32 m0, s48
	v_lshl_add_u64 v[166:167], v[230:231], 0, s[14:15]
	s_barrier
	ds_read_b128 v[144:147], v190 offset:49152
	ds_read_b128 v[148:151], v190 offset:50176
	ds_read_b128 v[152:155], v190 offset:51200
	ds_read_b128 v[156:159], v190 offset:52224
	ds_read_b128 v[180:183], v190 offset:53248
	ds_read_b128 v[184:187], v190 offset:54272
	ds_read_b128 v[194:197], v190 offset:55296
	ds_read_b128 v[198:201], v190 offset:56320
	global_load_lds_dwordx4 v[166:167], off
	v_lshl_add_u64 v[166:167], v[232:233], 0, s[14:15]
	s_mov_b32 m0, s49
	s_nop 0
	global_load_lds_dwordx4 v[166:167], off
	s_barrier
	s_waitcnt lgkmcnt(0)
	s_setprio 1
	s_waitcnt lgkmcnt(0)
	v_mfma_f32_16x16x32_bf16 v[60:63], v[128:131], v[144:147], v[60:63]
	v_mfma_f32_16x16x32_bf16 v[56:59], v[136:139], v[144:147], v[56:59]
	v_mfma_f32_16x16x32_bf16 v[52:55], v[128:131], v[152:155], v[52:55]
	v_mfma_f32_16x16x32_bf16 v[40:43], v[136:139], v[152:155], v[40:43]
	v_mfma_f32_16x16x32_bf16 v[36:39], v[128:131], v[180:183], v[36:39]
	v_mfma_f32_16x16x32_bf16 v[24:27], v[136:139], v[180:183], v[24:27]
	v_mfma_f32_16x16x32_bf16 v[20:23], v[128:131], v[194:197], v[20:23]
	v_mfma_f32_16x16x32_bf16 v[8:11], v[136:139], v[194:197], v[8:11]
	v_mfma_f32_16x16x32_bf16 v[60:63], v[132:135], v[148:151], v[60:63]
	v_mfma_f32_16x16x32_bf16 v[56:59], v[140:143], v[148:151], v[56:59]
	v_mfma_f32_16x16x32_bf16 v[52:55], v[132:135], v[156:159], v[52:55]
	v_mfma_f32_16x16x32_bf16 v[40:43], v[140:143], v[156:159], v[40:43]
	v_mfma_f32_16x16x32_bf16 v[36:39], v[132:135], v[184:187], v[36:39]
	v_mfma_f32_16x16x32_bf16 v[24:27], v[140:143], v[184:187], v[24:27]
	v_mfma_f32_16x16x32_bf16 v[20:23], v[132:135], v[198:201], v[20:23]
	v_mfma_f32_16x16x32_bf16 v[8:11], v[140:143], v[198:201], v[8:11]
	s_setprio 0
	s_barrier
	s_add_u32 s36, s36, 0x80080
	s_addc_u32 s37, s37, 0
	s_add_i32 s38, s38, s42
	v_lshl_add_u64 v[128:129], s[36:37], 0, v[172:173]
	s_mov_b32 m0, s38
	s_nop 0
	global_load_lds_dwordx4 v[128:129], off
	v_lshl_add_u64 v[128:129], s[36:37], 0, v[174:175]
	s_add_i32 m0, s38, 0x2000
	s_nop 0
	global_load_lds_dwordx4 v[128:129], off
	s_waitcnt vmcnt(6)
	s_barrier
	s_setprio 1
	v_mfma_f32_16x16x32_bf16 v[48:51], v[202:205], v[144:147], v[48:51]
	v_mfma_f32_16x16x32_bf16 v[44:47], v[222:225], v[144:147], v[44:47]
	v_mfma_f32_16x16x32_bf16 v[32:35], v[202:205], v[152:155], v[32:35]
	v_mfma_f32_16x16x32_bf16 v[28:31], v[222:225], v[152:155], v[28:31]
	v_mfma_f32_16x16x32_bf16 v[16:19], v[202:205], v[180:183], v[16:19]
	v_mfma_f32_16x16x32_bf16 v[12:15], v[222:225], v[180:183], v[12:15]
	v_mfma_f32_16x16x32_bf16 v[4:7], v[202:205], v[194:197], v[4:7]
	v_mfma_f32_16x16x32_bf16 v[0:3], v[222:225], v[194:197], v[0:3]
	v_mfma_f32_16x16x32_bf16 v[48:51], v[206:209], v[148:151], v[48:51]
	v_mfma_f32_16x16x32_bf16 v[44:47], v[226:229], v[148:151], v[44:47]
	v_mfma_f32_16x16x32_bf16 v[32:35], v[206:209], v[156:159], v[32:35]
	v_mfma_f32_16x16x32_bf16 v[28:31], v[226:229], v[156:159], v[28:31]
	v_mfma_f32_16x16x32_bf16 v[16:19], v[206:209], v[184:187], v[16:19]
	v_mfma_f32_16x16x32_bf16 v[12:15], v[226:229], v[184:187], v[12:15]
	v_mfma_f32_16x16x32_bf16 v[4:7], v[206:209], v[198:201], v[4:7]
	v_mfma_f32_16x16x32_bf16 v[0:3], v[226:229], v[198:201], v[0:3]
	s_setprio 0
	s_add_u32 s4, s4, 0x100
	s_addc_u32 s5, s5, 0
	s_add_u32 s60, s60, 0x100
	s_addc_u32 s61, s61, 0
	s_cmp_ge_i32 s62, s17
	s_mov_b32 s36, s62
	s_barrier
	s_cbranch_scc0 .LBB0_1024
	v_mov_b32_e32 v128, v210
	v_mov_b32_e32 v129, v169
	s_cmp_lt_i32 s12, 0
	v_lshl_add_u32 v128, v128, 4, v129
	v_ashrrev_i32_e32 v166, 2, v128
	v_and_b32_e32 v160, 3, v129
	v_and_b32_e32 v128, -4, v128
	v_lshl_add_u32 v193, v160, 6, v128
	s_mov_b64 s[4:5], -1
	s_cbranch_scc0 .LBB0_1043
	s_lshl_b32 s4, s30, 8
	v_lshl_or_b32 v128, v160, 2, s4
	s_lshl_b32 s4, s34, 8
	v_or_b32_e32 v180, s47, v128
	s_add_i32 s4, s4, s46
	v_readlane_b32 s60, v254, 6
	v_ashrrev_i32_e32 v181, 31, v180
	v_add_u32_e32 v184, s4, v166
	s_cmp_lt_i32 s34, 32
	v_readlane_b32 s61, v254, 7
	v_lshlrev_b64 v[128:129], 2, v[180:181]
	v_readlane_b32 s62, v254, 8
	v_readlane_b32 s63, v254, 9
	v_readlane_b32 s64, v254, 10
	v_readlane_b32 s65, v254, 11
	v_readlane_b32 s66, v254, 12
	v_readlane_b32 s67, v254, 13
	v_readlane_b32 s68, v254, 14
	v_readlane_b32 s69, v254, 15
	v_readlane_b32 s70, v254, 16
	v_readlane_b32 s71, v254, 17
	v_readlane_b32 s72, v254, 18
	v_readlane_b32 s73, v254, 19
	v_readlane_b32 s74, v254, 20
	v_readlane_b32 s75, v254, 21
	s_cselect_b32 s5, s61, s51
	s_cselect_b32 s4, s60, s50
	v_ashrrev_i32_e32 v185, 31, v184
	v_lshl_add_u64 v[182:183], s[4:5], 0, v[128:129]
	v_lshlrev_b64 v[130:131], 13, v[184:185]
	v_readlane_b32 s60, v254, 22
	v_lshl_add_u64 v[136:137], v[182:183], 0, v[130:131]
	v_readlane_b32 s61, v254, 23
	v_readlane_b32 s68, v254, 30
	v_readlane_b32 s69, v254, 31
	global_load_dwordx4 v[196:199], v[136:137], off nt
	global_load_dwordx4 v[200:203], v[136:137], off offset:64 nt
	global_load_dwordx4 v[204:207], v[136:137], off offset:512 nt
	s_mov_b64 s[60:61], s[68:69]
	v_lshl_add_u64 v[138:139], s[60:61], 0, v[128:129]
	global_load_dwordx4 v[140:143], v[138:139], off
	global_load_dwordx4 v[132:135], v[138:139], off offset:64
	global_load_dwordx4 v[128:131], v[138:139], off offset:512
	global_load_dwordx4 v[222:225], v[136:137], off offset:576 nt
	v_and_b32_e32 v145, 64, v192
	global_load_dwordx4 v[136:139], v[138:139], off offset:576
	v_xor_b32_e32 v144, 1, v192
	v_add_u32_e32 v194, 64, v145
	v_add_u32_e32 v186, 16, v184
	v_cmp_lt_i32_e64 s[4:5], v144, v194
	v_ashrrev_i32_e32 v187, 31, v186
	ds_bpermute_b32 v188, v193, v124
	v_cndmask_b32_e64 v195, v192, v144, s[4:5]
	v_lshlrev_b64 v[144:145], 13, v[186:187]
	v_lshl_add_u64 v[144:145], v[182:183], 0, v[144:145]
	global_load_dwordx4 v[156:159], v[144:145], off nt
	global_load_dwordx4 v[152:155], v[144:145], off offset:64 nt
	global_load_dwordx4 v[148:151], v[144:145], off offset:512 nt
	s_nop 0
	global_load_dwordx4 v[144:147], v[144:145], off offset:576 nt
	ds_bpermute_b32 v189, v193, v125
	ds_bpermute_b32 v208, v193, v126
	ds_bpermute_b32 v209, v193, v127
	ds_bpermute_b32 v226, v193, v120
	ds_bpermute_b32 v227, v193, v121
	ds_bpermute_b32 v228, v193, v122
	ds_bpermute_b32 v229, v193, v123
	ds_bpermute_b32 v230, v193, v112
	ds_bpermute_b32 v231, v193, v113
	v_readlane_b32 s64, v254, 26
	v_readlane_b32 s65, v254, 27
	v_readlane_b32 s66, v254, 28
	v_readlane_b32 s67, v254, 29
	v_readlane_b32 s72, v254, 34
	v_readlane_b32 s73, v254, 35
	v_readlane_b32 s74, v254, 36
	v_readlane_b32 s75, v254, 37
	s_mov_b64 s[64:65], s[72:73]
	ds_bpermute_b32 v232, v193, v114
	ds_bpermute_b32 v233, v193, v115
	v_lshlrev_b64 v[234:235], 11, v[184:185]
	s_mov_b64 s[66:67], s[74:75]
	v_lshl_add_u64 v[234:235], v[234:235], 0, v[180:181]
	v_xor_b32_e32 v167, 2, v192
	v_lshl_add_u64 v[236:237], v[234:235], 2, s[66:67]
	v_readlane_b32 s2, v254, 54
	v_cmp_lt_i32_e64 s[4:5], v167, v194
	v_lshlrev_b32_e32 v194, 2, v195
	v_lshlrev_b64 v[234:235], 1, v[234:235]
	v_readlane_b32 s3, v254, 55
	v_or_b32_e32 v240, 32, v234
	v_mov_b32_e32 v241, v235
	v_lshl_add_u64 v[238:239], s[2:3], 0, v[234:235]
	v_lshl_add_u64 v[240:241], s[2:3], 0, v[240:241]
	v_cndmask_b32_e64 v167, v192, v167, s[4:5]
	v_lshlrev_b32_e32 v167, 2, v167
	v_cmp_eq_u32_e32 vcc, 0, v160
	v_readlane_b32 s62, v254, 24
	v_readlane_b32 s63, v254, 25
	v_readlane_b32 s70, v254, 32
	v_readlane_b32 s71, v254, 33
	s_waitcnt vmcnt(0) lgkmcnt(0)
	v_pk_add_f32 v[198:199], v[198:199], v[208:209]
	v_pk_add_f32 v[196:197], v[196:197], v[188:189]
	v_pk_add_f32 v[202:203], v[202:203], v[228:229]
	v_pk_add_f32 v[200:201], v[200:201], v[226:227]
	v_pk_add_f32 v[204:205], v[204:205], v[230:231]
	v_mul_f32_e32 v195, v197, v197
	v_mul_f32_e32 v221, v199, v199
	global_store_dwordx4 v[236:237], v[196:199], off
	v_pk_mul_f32 v[188:189], v[142:143], v[198:199]
	v_pk_mul_f32 v[208:209], v[140:141], v[196:197]
	v_mul_f32_e32 v199, v201, v201
	v_mul_f32_e32 v230, v203, v203
	v_pk_mul_f32 v[226:227], v[134:135], v[202:203]
	v_pk_mul_f32 v[228:229], v[132:133], v[200:201]
	v_fmac_f32_e32 v195, v196, v196
	v_fmac_f32_e32 v221, v198, v198
	v_cvt_pk_bf16_f32 v196, v208, v209
	v_cvt_pk_bf16_f32 v197, v188, v189
	v_fmac_f32_e32 v199, v200, v200
	v_fmac_f32_e32 v230, v202, v202
	v_pk_add_f32 v[206:207], v[206:207], v[232:233]
	v_cvt_pk_bf16_f32 v188, v228, v229
	v_cvt_pk_bf16_f32 v189, v226, v227
	v_add_f32_e32 v195, v195, v221
	global_store_dwordx2 v[238:239], v[196:197], off
	v_add_f32_e32 v196, v199, v230
	global_store_dwordx4 v[236:237], v[200:203], off offset:64
	global_store_dwordx2 v[240:241], v[188:189], off
	v_add_f32_e32 v188, v195, v196
	v_mul_f32_e32 v189, v205, v205
	v_mul_f32_e32 v195, v207, v207
	v_fmac_f32_e32 v189, v204, v204
	v_fmac_f32_e32 v195, v206, v206
	ds_bpermute_b32 v200, v193, v108
	ds_bpermute_b32 v198, v193, v110
	ds_bpermute_b32 v199, v193, v111
	ds_bpermute_b32 v201, v193, v109
	v_add_f32_e32 v189, v189, v195
	v_add_f32_e32 v195, v188, v189
	v_pk_mul_f32 v[188:189], v[130:131], v[206:207]
	v_pk_mul_f32 v[196:197], v[128:129], v[204:205]
	global_store_dwordx4 v[236:237], v[204:207], off offset:512
	v_cvt_pk_bf16_f32 v196, v196, v197
	v_cvt_pk_bf16_f32 v197, v188, v189
	v_or_b32_e32 v188, 0x100, v234
	v_mov_b32_e32 v189, v235
	v_lshl_add_u64 v[188:189], s[2:3], 0, v[188:189]
	global_store_dwordx2 v[188:189], v[196:197], off
	s_waitcnt lgkmcnt(1)
	v_pk_add_f32 v[198:199], v[224:225], v[198:199]
	s_waitcnt lgkmcnt(0)
	v_pk_add_f32 v[196:197], v[222:223], v[200:201]
	v_mul_f32_e32 v189, v199, v199
	v_mul_f32_e32 v188, v197, v197
	v_fmac_f32_e32 v188, v196, v196
	v_fmac_f32_e32 v189, v198, v198
	v_add_f32_e32 v188, v188, v189
	v_add_f32_e32 v195, v195, v188
	ds_bpermute_b32 v200, v194, v195
	v_pk_mul_f32 v[188:189], v[136:137], v[196:197]
	global_store_dwordx4 v[236:237], v[196:199], off offset:576
	v_or_b32_e32 v234, 0x120, v234
	s_nop 0
	v_cvt_pk_bf16_f32 v196, v188, v189
	s_waitcnt lgkmcnt(0)
	v_add_f32_e32 v188, v195, v200
	ds_bpermute_b32 v189, v167, v188
	v_pk_mul_f32 v[198:199], v[138:139], v[198:199]
	s_nop 0
	v_cvt_pk_bf16_f32 v197, v198, v199
	v_lshl_add_u64 v[198:199], s[2:3], 0, v[234:235]
	global_store_dwordx2 v[198:199], v[196:197], off
	s_and_saveexec_b64 s[4:5], vcc
	s_cbranch_execz .LBB0_1028
	s_waitcnt lgkmcnt(0)
	v_add_f32_e32 v195, v188, v189
	s_lshl_b32 s36, s30, 2
	v_lshlrev_b64 v[188:189], 7, v[184:185]
	s_ashr_i32 s37, s36, 31
	v_lshl_add_u64 v[188:189], s[10:11], 0, v[188:189]
	v_lshl_add_u64 v[188:189], s[36:37], 2, v[188:189]
	s_lshl_b32 s36, s45, 2
	s_mov_b32 s37, s13
	v_lshl_add_u64 v[188:189], v[188:189], 0, s[36:37]
	global_store_dword v[188:189], v195, off

.LBB0_1030:
	s_or_b64 exec, exec, s[4:5]
	v_add_u32_e32 v188, 32, v184
	v_ashrrev_i32_e32 v189, 31, v188
	s_waitcnt lgkmcnt(0)
	v_lshlrev_b64 v[144:145], 13, v[188:189]
	v_lshl_add_u64 v[144:145], v[182:183], 0, v[144:145]
	global_load_dwordx4 v[196:199], v[144:145], off nt
	global_load_dwordx4 v[200:203], v[144:145], off offset:64 nt
	global_load_dwordx4 v[204:207], v[144:145], off offset:512 nt
	global_load_dwordx4 v[222:225], v[144:145], off offset:576 nt
	v_add_u32_e32 v186, 48, v184
	v_ashrrev_i32_e32 v187, 31, v186
	v_lshlrev_b64 v[144:145], 13, v[186:187]
	v_lshl_add_u64 v[144:145], v[182:183], 0, v[144:145]
	global_load_dwordx4 v[156:159], v[144:145], off nt
	global_load_dwordx4 v[152:155], v[144:145], off offset:64 nt
	global_load_dwordx4 v[148:151], v[144:145], off offset:512 nt
	s_nop 0
	global_load_dwordx4 v[144:147], v[144:145], off offset:576 nt
	ds_bpermute_b32 v208, v193, v96
	ds_bpermute_b32 v209, v193, v97
	ds_bpermute_b32 v226, v193, v98
	ds_bpermute_b32 v227, v193, v99
	ds_bpermute_b32 v228, v193, v88
	ds_bpermute_b32 v229, v193, v89
	ds_bpermute_b32 v230, v193, v90
	ds_bpermute_b32 v231, v193, v91
	ds_bpermute_b32 v232, v193, v84
	ds_bpermute_b32 v233, v193, v85
	ds_bpermute_b32 v234, v193, v86
	ds_bpermute_b32 v235, v193, v87
	ds_bpermute_b32 v236, v193, v76
	ds_bpermute_b32 v237, v193, v77
	ds_bpermute_b32 v238, v193, v78
	ds_bpermute_b32 v239, v193, v79
	v_lshlrev_b64 v[240:241], 11, v[188:189]
	v_readlane_b32 s60, v254, 22
	v_lshl_add_u64 v[240:241], v[240:241], 0, v[180:181]
	v_readlane_b32 s74, v254, 36
	v_readlane_b32 s75, v254, 37
	v_readlane_b32 s2, v254, 54
	v_readlane_b32 s3, v254, 55
	v_lshl_add_u64 v[242:243], v[240:241], 2, s[74:75]
	v_lshlrev_b64 v[240:241], 1, v[240:241]
	v_lshl_add_u64 v[244:245], s[2:3], 0, v[240:241]
	v_or_b32_e32 v246, 32, v240
	v_mov_b32_e32 v247, v241
	v_or_b32_e32 v248, 0x100, v240
	v_lshl_add_u64 v[246:247], s[2:3], 0, v[246:247]
	v_or_b32_e32 v240, 0x120, v240
	v_mov_b32_e32 v249, v241
	v_readlane_b32 s61, v254, 23
	v_readlane_b32 s62, v254, 24
	v_readlane_b32 s63, v254, 25
	v_readlane_b32 s64, v254, 26
	v_readlane_b32 s65, v254, 27
	v_readlane_b32 s66, v254, 28
	v_readlane_b32 s67, v254, 29
	v_readlane_b32 s68, v254, 30
	v_readlane_b32 s69, v254, 31
	v_readlane_b32 s70, v254, 32
	v_readlane_b32 s71, v254, 33
	v_readlane_b32 s72, v254, 34
	v_readlane_b32 s73, v254, 35
	v_lshl_add_u64 v[248:249], s[2:3], 0, v[248:249]
	s_waitcnt vmcnt(7) lgkmcnt(12)
	v_pk_add_f32 v[198:199], v[198:199], v[226:227]
	v_pk_add_f32 v[196:197], v[196:197], v[208:209]
	s_waitcnt vmcnt(6) lgkmcnt(8)
	v_pk_add_f32 v[202:203], v[202:203], v[230:231]
	v_pk_add_f32 v[200:201], v[200:201], v[228:229]
	s_waitcnt vmcnt(5) lgkmcnt(4)
	v_pk_add_f32 v[206:207], v[206:207], v[234:235]
	v_pk_add_f32 v[204:205], v[204:205], v[232:233]
	s_waitcnt vmcnt(4) lgkmcnt(2)
	v_pk_add_f32 v[222:223], v[222:223], v[236:237]
	v_mul_f32_e32 v185, v197, v197
	v_mul_f32_e32 v195, v199, v199
	v_mul_f32_e32 v221, v201, v201
	v_mul_f32_e32 v236, v203, v203
	s_waitcnt lgkmcnt(0)
	v_pk_add_f32 v[224:225], v[224:225], v[238:239]
	v_pk_mul_f32 v[208:209], v[142:143], v[198:199]
	v_pk_mul_f32 v[226:227], v[140:141], v[196:197]
	v_mul_f32_e32 v237, v205, v205
	v_mul_f32_e32 v238, v207, v207
	v_fmac_f32_e32 v185, v196, v196
	v_fmac_f32_e32 v195, v198, v198
	v_fmac_f32_e32 v221, v200, v200
	v_fmac_f32_e32 v236, v202, v202
	global_store_dwordx4 v[242:243], v[196:199], off
	v_mul_f32_e32 v239, v223, v223
	v_mul_f32_e32 v250, v225, v225
	v_cvt_pk_bf16_f32 v196, v226, v227
	v_cvt_pk_bf16_f32 v197, v208, v209
	v_fmac_f32_e32 v237, v204, v204
	v_fmac_f32_e32 v238, v206, v206
	v_add_f32_e32 v185, v185, v195
	v_add_f32_e32 v195, v221, v236
	v_fmac_f32_e32 v239, v222, v222
	v_fmac_f32_e32 v250, v224, v224
	global_store_dwordx2 v[244:245], v[196:197], off
	v_add_f32_e32 v196, v237, v238
	v_add_f32_e32 v185, v185, v195
	v_add_f32_e32 v185, v185, v196
	v_add_f32_e32 v195, v239, v250
	v_add_f32_e32 v185, v185, v195
	ds_bpermute_b32 v195, v194, v185
	v_pk_mul_f32 v[228:229], v[134:135], v[202:203]
	v_pk_mul_f32 v[230:231], v[132:133], v[200:201]
	v_cvt_pk_bf16_f32 v199, v228, v229
	v_cvt_pk_bf16_f32 v198, v230, v231
	s_waitcnt lgkmcnt(0)
	v_add_f32_e32 v185, v185, v195
	ds_bpermute_b32 v195, v167, v185
	global_store_dwordx4 v[242:243], v[200:203], off offset:64
	global_store_dwordx2 v[246:247], v[198:199], off
	v_pk_mul_f32 v[196:197], v[138:139], v[224:225]
	v_pk_mul_f32 v[198:199], v[136:137], v[222:223]
	v_pk_mul_f32 v[232:233], v[130:131], v[206:207]
	v_pk_mul_f32 v[234:235], v[128:129], v[204:205]
	v_cvt_pk_bf16_f32 v198, v198, v199
	v_cvt_pk_bf16_f32 v199, v196, v197
	v_lshl_add_u64 v[196:197], s[2:3], 0, v[240:241]
	v_cvt_pk_bf16_f32 v208, v234, v235
	v_cvt_pk_bf16_f32 v209, v232, v233
	global_store_dwordx4 v[242:243], v[204:207], off offset:512
	global_store_dwordx2 v[248:249], v[208:209], off
	global_store_dwordx4 v[242:243], v[222:225], off offset:576
	global_store_dwordx2 v[196:197], v[198:199], off
	s_and_saveexec_b64 s[4:5], vcc
	s_cbranch_execz .LBB0_1032
	s_lshl_b32 s36, s30, 2
	v_lshlrev_b64 v[188:189], 7, v[188:189]
	s_ashr_i32 s37, s36, 31
	v_lshl_add_u64 v[188:189], s[10:11], 0, v[188:189]
	v_lshl_add_u64 v[188:189], s[36:37], 2, v[188:189]
	s_lshl_b32 s36, s45, 2
	s_mov_b32 s37, s13
	s_waitcnt lgkmcnt(0)
	v_add_f32_e32 v185, v185, v195
	v_lshl_add_u64 v[188:189], v[188:189], 0, s[36:37]
	global_store_dword v[188:189], v185, off

.LBB0_1034:
	s_or_b64 exec, exec, s[4:5]
	v_add_u32_e32 v188, 0x80, v184
	v_ashrrev_i32_e32 v189, 31, v188
	s_waitcnt lgkmcnt(0)
	v_lshlrev_b64 v[144:145], 13, v[188:189]
	v_lshl_add_u64 v[144:145], v[182:183], 0, v[144:145]
	global_load_dwordx4 v[196:199], v[144:145], off nt
	global_load_dwordx4 v[200:203], v[144:145], off offset:64 nt
	global_load_dwordx4 v[204:207], v[144:145], off offset:512 nt
	global_load_dwordx4 v[222:225], v[144:145], off offset:576 nt
	v_add_u32_e32 v186, 0x90, v184
	v_ashrrev_i32_e32 v187, 31, v186
	v_lshlrev_b64 v[144:145], 13, v[186:187]
	v_lshl_add_u64 v[144:145], v[182:183], 0, v[144:145]
	global_load_dwordx4 v[156:159], v[144:145], off nt
	global_load_dwordx4 v[152:155], v[144:145], off offset:64 nt
	global_load_dwordx4 v[148:151], v[144:145], off offset:512 nt
	s_nop 0
	global_load_dwordx4 v[144:147], v[144:145], off offset:576 nt
	ds_bpermute_b32 v208, v193, v60
	ds_bpermute_b32 v209, v193, v61
	ds_bpermute_b32 v226, v193, v62
	ds_bpermute_b32 v227, v193, v63
	ds_bpermute_b32 v228, v193, v56
	ds_bpermute_b32 v229, v193, v57
	ds_bpermute_b32 v230, v193, v58
	ds_bpermute_b32 v231, v193, v59
	ds_bpermute_b32 v232, v193, v48
	ds_bpermute_b32 v233, v193, v49
	ds_bpermute_b32 v234, v193, v50
	ds_bpermute_b32 v235, v193, v51
	ds_bpermute_b32 v236, v193, v44
	ds_bpermute_b32 v237, v193, v45
	ds_bpermute_b32 v238, v193, v46
	ds_bpermute_b32 v239, v193, v47
	v_lshlrev_b64 v[240:241], 11, v[188:189]
	v_readlane_b32 s60, v254, 22
	v_lshl_add_u64 v[240:241], v[240:241], 0, v[180:181]
	v_readlane_b32 s74, v254, 36
	v_readlane_b32 s75, v254, 37
	v_readlane_b32 s2, v254, 54
	v_readlane_b32 s3, v254, 55
	v_lshl_add_u64 v[242:243], v[240:241], 2, s[74:75]
	v_lshlrev_b64 v[240:241], 1, v[240:241]
	v_lshl_add_u64 v[244:245], s[2:3], 0, v[240:241]
	v_or_b32_e32 v246, 32, v240
	v_mov_b32_e32 v247, v241
	v_or_b32_e32 v248, 0x100, v240
	v_lshl_add_u64 v[246:247], s[2:3], 0, v[246:247]
	v_or_b32_e32 v240, 0x120, v240
	v_mov_b32_e32 v249, v241
	v_readlane_b32 s61, v254, 23
	v_readlane_b32 s62, v254, 24
	v_readlane_b32 s63, v254, 25
	v_readlane_b32 s64, v254, 26
	v_readlane_b32 s65, v254, 27
	v_readlane_b32 s66, v254, 28
	v_readlane_b32 s67, v254, 29
	v_readlane_b32 s68, v254, 30
	v_readlane_b32 s69, v254, 31
	v_readlane_b32 s70, v254, 32
	v_readlane_b32 s71, v254, 33
	v_readlane_b32 s72, v254, 34
	v_readlane_b32 s73, v254, 35
	v_lshl_add_u64 v[248:249], s[2:3], 0, v[248:249]
	s_waitcnt vmcnt(7) lgkmcnt(12)
	v_pk_add_f32 v[198:199], v[198:199], v[226:227]
	v_pk_add_f32 v[196:197], v[196:197], v[208:209]
	s_waitcnt vmcnt(6) lgkmcnt(8)
	v_pk_add_f32 v[202:203], v[202:203], v[230:231]
	v_pk_add_f32 v[200:201], v[200:201], v[228:229]
	s_waitcnt vmcnt(5) lgkmcnt(4)
	v_pk_add_f32 v[206:207], v[206:207], v[234:235]
	v_pk_add_f32 v[204:205], v[204:205], v[232:233]
	s_waitcnt vmcnt(4) lgkmcnt(2)
	v_pk_add_f32 v[222:223], v[222:223], v[236:237]
	v_mul_f32_e32 v185, v197, v197
	v_mul_f32_e32 v195, v199, v199
	v_mul_f32_e32 v221, v201, v201
	v_mul_f32_e32 v236, v203, v203
	s_waitcnt lgkmcnt(0)
	v_pk_add_f32 v[224:225], v[224:225], v[238:239]
	v_pk_mul_f32 v[208:209], v[142:143], v[198:199]
	v_pk_mul_f32 v[226:227], v[140:141], v[196:197]
	v_mul_f32_e32 v237, v205, v205
	v_mul_f32_e32 v238, v207, v207
	v_fmac_f32_e32 v185, v196, v196
	v_fmac_f32_e32 v195, v198, v198
	v_fmac_f32_e32 v221, v200, v200
	v_fmac_f32_e32 v236, v202, v202
	global_store_dwordx4 v[242:243], v[196:199], off
	v_mul_f32_e32 v239, v223, v223
	v_mul_f32_e32 v250, v225, v225
	v_cvt_pk_bf16_f32 v196, v226, v227
	v_cvt_pk_bf16_f32 v197, v208, v209
	v_fmac_f32_e32 v237, v204, v204
	v_fmac_f32_e32 v238, v206, v206
	v_add_f32_e32 v185, v185, v195
	v_add_f32_e32 v195, v221, v236
	v_fmac_f32_e32 v239, v222, v222
	v_fmac_f32_e32 v250, v224, v224
	global_store_dwordx2 v[244:245], v[196:197], off
	v_add_f32_e32 v196, v237, v238
	v_add_f32_e32 v185, v185, v195
	v_add_f32_e32 v185, v185, v196
	v_add_f32_e32 v195, v239, v250
	v_add_f32_e32 v185, v185, v195
	ds_bpermute_b32 v195, v194, v185
	v_pk_mul_f32 v[228:229], v[134:135], v[202:203]
	v_pk_mul_f32 v[230:231], v[132:133], v[200:201]
	v_cvt_pk_bf16_f32 v199, v228, v229
	v_cvt_pk_bf16_f32 v198, v230, v231
	s_waitcnt lgkmcnt(0)
	v_add_f32_e32 v185, v185, v195
	ds_bpermute_b32 v195, v167, v185
	global_store_dwordx4 v[242:243], v[200:203], off offset:64
	global_store_dwordx2 v[246:247], v[198:199], off
	v_pk_mul_f32 v[196:197], v[138:139], v[224:225]
	v_pk_mul_f32 v[198:199], v[136:137], v[222:223]
	v_pk_mul_f32 v[232:233], v[130:131], v[206:207]
	v_pk_mul_f32 v[234:235], v[128:129], v[204:205]
	v_cvt_pk_bf16_f32 v198, v198, v199
	v_cvt_pk_bf16_f32 v199, v196, v197
	v_lshl_add_u64 v[196:197], s[2:3], 0, v[240:241]
	v_cvt_pk_bf16_f32 v208, v234, v235
	v_cvt_pk_bf16_f32 v209, v232, v233
	global_store_dwordx4 v[242:243], v[204:207], off offset:512
	global_store_dwordx2 v[248:249], v[208:209], off
	global_store_dwordx4 v[242:243], v[222:225], off offset:576
	global_store_dwordx2 v[196:197], v[198:199], off
	s_and_saveexec_b64 s[4:5], vcc
	s_cbranch_execz .LBB0_1036
	s_lshl_b32 s36, s30, 2
	v_lshlrev_b64 v[188:189], 7, v[188:189]
	s_ashr_i32 s37, s36, 31
	v_lshl_add_u64 v[188:189], s[10:11], 0, v[188:189]
	v_lshl_add_u64 v[188:189], s[36:37], 2, v[188:189]
	s_lshl_b32 s36, s45, 2
	s_mov_b32 s37, s13
	s_waitcnt lgkmcnt(0)
	v_add_f32_e32 v185, v185, v195
	v_lshl_add_u64 v[188:189], v[188:189], 0, s[36:37]
	global_store_dword v[188:189], v185, off

.LBB0_1038:
	s_or_b64 exec, exec, s[4:5]
	v_add_u32_e32 v186, 0xa0, v184
	v_ashrrev_i32_e32 v187, 31, v186
	s_waitcnt lgkmcnt(0)
	v_lshlrev_b64 v[144:145], 13, v[186:187]
	v_lshl_add_u64 v[144:145], v[182:183], 0, v[144:145]
	global_load_dwordx4 v[196:199], v[144:145], off nt
	global_load_dwordx4 v[200:203], v[144:145], off offset:64 nt
	global_load_dwordx4 v[204:207], v[144:145], off offset:512 nt
	global_load_dwordx4 v[222:225], v[144:145], off offset:576 nt
	v_add_u32_e32 v184, 0xb0, v184
	v_ashrrev_i32_e32 v185, 31, v184
	v_lshlrev_b64 v[144:145], 13, v[184:185]
	v_lshl_add_u64 v[144:145], v[182:183], 0, v[144:145]
	global_load_dwordx4 v[156:159], v[144:145], off nt
	global_load_dwordx4 v[152:155], v[144:145], off offset:64 nt
	global_load_dwordx4 v[148:151], v[144:145], off offset:512 nt
	s_nop 0
	global_load_dwordx4 v[144:147], v[144:145], off offset:576 nt
	ds_bpermute_b32 v188, v193, v36
	ds_bpermute_b32 v189, v193, v37
	ds_bpermute_b32 v208, v193, v38
	ds_bpermute_b32 v209, v193, v39
	ds_bpermute_b32 v226, v193, v24
	ds_bpermute_b32 v227, v193, v25
	ds_bpermute_b32 v228, v193, v26
	ds_bpermute_b32 v229, v193, v27
	ds_bpermute_b32 v182, v193, v16
	ds_bpermute_b32 v183, v193, v17
	ds_bpermute_b32 v230, v193, v18
	ds_bpermute_b32 v231, v193, v19
	ds_bpermute_b32 v232, v193, v12
	ds_bpermute_b32 v233, v193, v13
	ds_bpermute_b32 v234, v193, v14
	ds_bpermute_b32 v235, v193, v15
	v_lshlrev_b64 v[236:237], 11, v[186:187]
	v_readlane_b32 s60, v254, 22
	v_lshl_add_u64 v[236:237], v[236:237], 0, v[180:181]
	v_readlane_b32 s74, v254, 36
	v_readlane_b32 s75, v254, 37
	v_readlane_b32 s2, v254, 54
	v_readlane_b32 s3, v254, 55
	v_lshl_add_u64 v[238:239], v[236:237], 2, s[74:75]
	v_lshlrev_b64 v[236:237], 1, v[236:237]
	v_lshl_add_u64 v[240:241], s[2:3], 0, v[236:237]
	v_or_b32_e32 v242, 32, v236
	v_mov_b32_e32 v243, v237
	v_lshl_add_u64 v[242:243], s[2:3], 0, v[242:243]
	v_or_b32_e32 v244, 0x100, v236
	v_mov_b32_e32 v245, v237
	v_lshl_add_u64 v[244:245], s[2:3], 0, v[244:245]
	v_or_b32_e32 v236, 0x120, v236
	v_readlane_b32 s61, v254, 23
	v_readlane_b32 s62, v254, 24
	v_readlane_b32 s63, v254, 25
	v_readlane_b32 s64, v254, 26
	v_readlane_b32 s65, v254, 27
	v_readlane_b32 s66, v254, 28
	v_readlane_b32 s67, v254, 29
	v_readlane_b32 s68, v254, 30
	v_readlane_b32 s69, v254, 31
	v_readlane_b32 s70, v254, 32
	v_readlane_b32 s71, v254, 33
	v_readlane_b32 s72, v254, 34
	v_readlane_b32 s73, v254, 35
	s_waitcnt vmcnt(7) lgkmcnt(12)
	v_pk_add_f32 v[198:199], v[198:199], v[208:209]
	v_pk_add_f32 v[196:197], v[196:197], v[188:189]
	s_waitcnt vmcnt(6) lgkmcnt(8)
	v_pk_add_f32 v[202:203], v[202:203], v[228:229]
	v_pk_add_f32 v[200:201], v[200:201], v[226:227]
	s_waitcnt vmcnt(5) lgkmcnt(4)
	v_pk_add_f32 v[206:207], v[206:207], v[230:231]
	v_pk_add_f32 v[204:205], v[204:205], v[182:183]
	s_waitcnt vmcnt(4) lgkmcnt(2)
	v_pk_add_f32 v[222:223], v[222:223], v[232:233]
	v_mul_f32_e32 v195, v197, v197
	v_mul_f32_e32 v221, v199, v199
	global_store_dwordx4 v[238:239], v[196:199], off
	v_pk_mul_f32 v[182:183], v[142:143], v[198:199]
	v_pk_mul_f32 v[188:189], v[140:141], v[196:197]
	v_mul_f32_e32 v199, v201, v201
	v_mul_f32_e32 v232, v203, v203
	s_waitcnt lgkmcnt(0)
	v_pk_add_f32 v[224:225], v[224:225], v[234:235]
	v_pk_mul_f32 v[208:209], v[134:135], v[202:203]
	v_pk_mul_f32 v[226:227], v[132:133], v[200:201]
	v_mul_f32_e32 v233, v205, v205
	v_mul_f32_e32 v234, v207, v207
	v_fmac_f32_e32 v195, v196, v196
	v_fmac_f32_e32 v221, v198, v198
	v_cvt_pk_bf16_f32 v188, v188, v189
	v_cvt_pk_bf16_f32 v189, v182, v183
	v_fmac_f32_e32 v199, v200, v200
	v_fmac_f32_e32 v232, v202, v202
	v_mul_f32_e32 v235, v223, v223
	v_mul_f32_e32 v246, v225, v225
	v_cvt_pk_bf16_f32 v182, v226, v227
	v_cvt_pk_bf16_f32 v183, v208, v209
	v_fmac_f32_e32 v233, v204, v204
	v_fmac_f32_e32 v234, v206, v206
	v_add_f32_e32 v195, v195, v221
	global_store_dwordx2 v[240:241], v[188:189], off
	v_add_f32_e32 v188, v199, v232
	v_fmac_f32_e32 v235, v222, v222
	v_fmac_f32_e32 v246, v224, v224
	global_store_dwordx4 v[238:239], v[200:203], off offset:64
	global_store_dwordx2 v[242:243], v[182:183], off
	v_add_f32_e32 v182, v233, v234
	v_add_f32_e32 v183, v195, v188
	v_pk_mul_f32 v[228:229], v[130:131], v[206:207]
	v_add_f32_e32 v182, v183, v182
	v_add_f32_e32 v183, v235, v246
	v_pk_mul_f32 v[230:231], v[128:129], v[204:205]
	v_cvt_pk_bf16_f32 v197, v228, v229
	v_add_f32_e32 v195, v182, v183
	v_cvt_pk_bf16_f32 v196, v230, v231
	global_store_dwordx4 v[238:239], v[204:207], off offset:512
	global_store_dwordx2 v[244:245], v[196:197], off
	ds_bpermute_b32 v197, v194, v195
	v_pk_mul_f32 v[182:183], v[136:137], v[222:223]
	v_pk_mul_f32 v[188:189], v[138:139], v[224:225]
	v_cvt_pk_bf16_f32 v196, v182, v183
	global_store_dwordx4 v[238:239], v[222:225], off offset:576
	s_waitcnt lgkmcnt(0)
	v_add_f32_e32 v182, v195, v197
	ds_bpermute_b32 v183, v167, v182
	v_cvt_pk_bf16_f32 v197, v188, v189
	v_lshl_add_u64 v[188:189], s[2:3], 0, v[236:237]
	global_store_dwordx2 v[188:189], v[196:197], off
	s_and_saveexec_b64 s[4:5], vcc
	s_cbranch_execz .LBB0_1040
	s_waitcnt lgkmcnt(0)
	v_add_f32_e32 v188, v182, v183
	s_lshl_b32 s36, s30, 2
	v_lshlrev_b64 v[182:183], 7, v[186:187]
	s_ashr_i32 s37, s36, 31
	v_lshl_add_u64 v[182:183], s[10:11], 0, v[182:183]
	v_lshl_add_u64 v[182:183], s[36:37], 2, v[182:183]
	s_lshl_b32 s36, s45, 2
	s_mov_b32 s37, s13
	v_lshl_add_u64 v[182:183], v[182:183], 0, s[36:37]
	global_store_dword v[182:183], v188, off

.LBB0_1172:
	v_readlane_b32 s2, v254, 62
	s_mul_hi_u32 s2, s2, 0x5d8
	v_readlane_b32 s4, v254, 63
	s_mul_i32 s2, s2, s4
	s_sub_i32 s2, 0x5d8, s2
	s_sub_i32 s3, s2, s4
	s_cmp_ge_u32 s2, s4
	s_cselect_b32 s2, s3, s2
	s_sub_i32 s3, s2, s4
	s_cmp_ge_u32 s2, s4
	s_cselect_b32 s2, s3, s2
	s_cmp_lg_u32 s2, 0
	s_cbranch_scc0 .LBB0_1180
	v_readlane_b32 s3, v254, 0
	s_cmp_lt_i32 s3, s2
	s_cbranch_scc1 .LBB0_1179
	v_readlane_b32 s3, v254, 0
	s_sub_i32 s3, s3, s2
	s_lshl_b32 s3, s3, 3
	v_readlane_b32 s4, v254, 44
	s_add_i32 s10, s3, s4
	s_cmpk_gt_u32 s10, 0x15ff
	s_cbranch_scc1 .LBB0_1179
	s_mov_b32 s4, s10
	s_sub_i32 s5, s76, s2
	s_lshl_b32 s5, s5, 3
	v_readlane_b32 s11, v254, 44
	v_and_b32_e32 v1, 31, v170
	v_lshlrev_b32_e32 v1, 2, v1
	v_lshrrev_b32_e32 v0, 5, v170
	s_mulk_i32 s11, 0x2200
	v_mul_u32_u24_e32 v2, 0x2000, v0
	v_add_u32_e32 v2, v2, v1
	s_mov_b32 s12, 0x4000
	v_add_u32_e32 v3, s12, v2
	v_add_u32_e32 v4, s12, v3
	v_add_u32_e32 v5, s12, v4
	v_add_u32_e32 v6, s12, v5
	v_add_u32_e32 v7, s12, v6
	v_add_u32_e32 v8, s12, v7
	v_add_u32_e32 v9, s12, v8
	v_mul_u32_u24_e32 v16, 0x84, v0
	v_add3_u32 v10, s11, v16, v1
	v_and_b32_e32 v17, 7, v170
	v_lshrrev_b32_e32 v18, 3, v170
	v_mul_u32_u24_e32 v19, 0x420, v17
	v_lshlrev_b32_e32 v20, 2, v18
	v_add3_u32 v11, s11, v19, v20
	v_mul_u32_u24_e32 v21, 0x2c00, v18
	v_lshl_add_u32 v12, v17, 4, v21
	s_mov_b32 s12, 0x16000
	v_add_u32_e32 v13, s12, v12
	v_add_u32_e32 v14, s12, v13
	v_add_u32_e32 v15, s12, v14
	s_mov_b32 s13, 0
.Lp4d_top:
	s_and_b32 s11, s4, 0xffffffc0
	s_and_b32 s12, s4, 63
	s_lshl_b32 s2, s11, 13
	s_lshl_b32 s10, s12, 7
	s_add_u32 s2, s2, s10
	s_mul_i32 s10, s12, 0x58000
	s_lshl_b32 s11, s11, 1
	s_add_u32 s10, s10, s11
	s_add_u32 s10, s10, 0x6600000
	v_readlane_b32 s20, v254, 34
	v_readlane_b32 s21, v254, 35
	v_readlane_b32 s16, v254, 2
	v_readlane_b32 s17, v254, 3
	s_add_u32 s20, s20, s2
	s_addc_u32 s21, s21, 0
	s_add_u32 s16, s16, s10
	s_addc_u32 s17, s17, 0
	s_add_u32 s22, s20, 0x20000
	s_addc_u32 s23, s21, 0
	s_add_u32 s24, s22, 0x20000
	s_addc_u32 s25, s23, 0
	s_add_u32 s26, s24, 0x20000
	s_addc_u32 s27, s25, 0
	global_load_dword v32, v2, s[20:21] nt
	global_load_dword v33, v3, s[20:21] nt
	global_load_dword v34, v4, s[20:21] nt
	global_load_dword v35, v5, s[20:21] nt
	global_load_dword v36, v6, s[20:21] nt
	global_load_dword v37, v7, s[20:21] nt
	global_load_dword v38, v8, s[20:21] nt
	global_load_dword v39, v9, s[20:21] nt
	global_load_dword v40, v2, s[22:23] nt
	global_load_dword v41, v3, s[22:23] nt
	global_load_dword v42, v4, s[22:23] nt
	global_load_dword v43, v5, s[22:23] nt
	global_load_dword v44, v6, s[22:23] nt
	global_load_dword v45, v7, s[22:23] nt
	global_load_dword v46, v8, s[22:23] nt
	global_load_dword v47, v9, s[22:23] nt
	global_load_dword v48, v2, s[24:25] nt
	global_load_dword v49, v3, s[24:25] nt
	global_load_dword v50, v4, s[24:25] nt
	global_load_dword v51, v5, s[24:25] nt
	global_load_dword v52, v6, s[24:25] nt
	global_load_dword v53, v7, s[24:25] nt
	global_load_dword v54, v8, s[24:25] nt
	global_load_dword v55, v9, s[24:25] nt
	global_load_dword v56, v2, s[26:27] nt
	global_load_dword v57, v3, s[26:27] nt
	global_load_dword v58, v4, s[26:27] nt
	global_load_dword v59, v5, s[26:27] nt
	global_load_dword v60, v6, s[26:27] nt
	global_load_dword v61, v7, s[26:27] nt
	global_load_dword v62, v8, s[26:27] nt
	global_load_dword v63, v9, s[26:27] nt
	s_mov_b32 s14, 1
	s_cmp_eq_u32 s13, 0
	s_cbranch_scc1 .Lp4d_ladder_first

.Lp4d_common:
	s_mov_b64 s[18:19], s[16:17]
	s_mov_b32 s13, 1
	s_add_i32 s4, s4, s5
	s_cmp_lt_i32 s4, 0x1600
	s_cbranch_scc1 .Lp4d_top
	s_mov_b32 s14, 0
	s_branch .Lp4d_finish

.LBB0_1238:
	s_or_b64 exec, exec, s[2:3]
	s_and_b64 vcc, exec, s[6:7]
	v_readfirstlane_b32 s22, v171
	s_waitcnt lgkmcnt(0)
	s_barrier
	s_cbranch_vccnz .LBB0_1266
	v_readlane_b32 s2, v254, 0
	s_nop 0
	s_cmpk_lt_u32 s2, 64
	s_cselect_b32 s3, 0x100, 0
	s_xor_b32 s2, s2, s3
	s_cmpk_lt_i32 s2, 0x100
	s_nop 0
	s_cselect_b32 s2, s2, 0
	s_ashr_i32 s3, s2, 31
	s_lshr_b32 s3, s3, 29
	s_add_i32 s5, s2, s3
	s_and_b32 s3, s5, -8
	s_sub_i32 s4, s2, s3
	s_cmp_gt_i32 s4, -1
	s_cbranch_scc0 .LBB0_1241
	s_lshl_b32 s6, s4, 5
	s_ashr_i32 s2, s5, 3
	s_cbranch_execz .LBB0_1242
	s_branch .LBB0_1243

.LBB0_1243:
	v_readlane_b32 s12, v254, 2
	v_readlane_b32 s13, v254, 3
	s_mov_b64 s[4:5], s[12:13]
	s_add_u32 s23, s4, 0x6600000
	s_addc_u32 s24, s5, 0
	s_add_i32 s2, s6, s2
	s_ashr_i32 s3, s2, 31
	s_lshr_b32 s3, s3, 26
	s_add_i32 s3, s2, s3
	s_ashr_i32 s6, s3, 6
	s_and_b32 s3, s3, 0xffc0
	s_sub_i32 s2, s2, s3
	s_bfe_i32 s3, s2, 0x80000
	s_bfe_u32 s3, s3, 0x3000c
	s_add_i32 s3, s2, s3
	s_bfe_i32 s7, s3, 0x80000
	s_and_b32 s3, s3, 0xf8
	s_sub_i32 s2, s2, s3
	s_lshl_b32 s6, s6, 3
	s_sext_i32_i8 s2, s2
	v_readlane_b32 s11, v254, 0
	s_nop 0
	s_cmpk_lt_u32 s11, 64
	s_cselect_b32 s12, 0x100, 0
	s_xor_b32 s11, s11, s12
	s_add_i32 s6, s6, s2
	s_add_i32 s2, s11, 0xffffff00
	s_lshr_b32 s5, s22, 6
	s_sext_i32_i16 s7, s7
	s_lshr_b32 s2, s2, 5
	s_nop 0
	s_lshr_b32 s4, s22, 8
	s_lshl_b32 s25, s5, 10
	s_ashr_i32 s7, s7, 3
	s_add_i32 s10, s2, 32
	s_cmpk_lt_i32 s11, 0x100
	s_cselect_b64 s[12:13], -1, 0
	s_and_b64 s[2:3], s[12:13], exec
	s_cselect_b32 s50, s6, s10
	s_bfe_u32 s6, s11, 0x30002
	s_and_b64 s[2:3], s[12:13], exec
	s_cselect_b32 s49, s7, s6
	s_and_b32 s2, s11, 3
	s_and_b64 s[6:7], s[12:13], exec
	s_mul_i32 s3, s2, 0xb00
	s_mul_i32 s7, s50, 0x2c0000
	s_cselect_b32 s3, 0, s3
	s_mul_hi_i32 s6, s50, 0x2c0000
	s_add_u32 s7, s0, s7
	s_mul_i32 s10, s49, 0x2c0000
	s_addc_u32 s6, s1, s6
	s_ashr_i32 s11, s10, 31
	s_add_u32 s10, s23, s10
	s_addc_u32 s11, s24, s11
	s_add_u32 s18, s10, s3
	v_mul_u32_u24_e32 v9, 0x2c00, v216
	s_addc_u32 s19, s11, 0
	s_add_i32 s26, s25, 0
	v_or_b32_e32 v140, v9, v215
	s_add_i32 m0, s26, 0x10000
	v_mul_u32_u24_e32 v8, 0x2c00, v217
	global_load_lds_dwordx4 v140, s[18:19]
	s_add_i32 m0, s26, 0x12000
	v_or_b32_e32 v142, v8, v215
	s_add_u32 s16, s7, s3
	global_load_lds_dwordx4 v142, s[18:19]
	s_addc_u32 s17, s6, 0
	s_mov_b32 m0, s26
	s_add_i32 s27, s26, 0x2000
	global_load_lds_dwordx4 v140, s[16:17]
	s_mov_b32 m0, s27
	s_add_u32 s6, s18, 0x160000
	global_load_lds_dwordx4 v142, s[16:17]
	s_addc_u32 s7, s19, 0
	s_add_i32 m0, s26, 0x14000
	v_mov_b32_e32 v145, 0
	global_load_lds_dwordx4 v140, s[6:7]
	s_add_i32 m0, s26, 0x16000
	v_mov_b32_e32 v141, v145
	global_load_lds_dwordx4 v142, s[6:7]
	s_add_u32 s6, s16, 0x160000
	s_addc_u32 s7, s17, 0
	s_add_i32 s28, s26, 0x4000
	s_mov_b32 m0, s28
	s_add_i32 s29, s26, 0x6000
	global_load_lds_dwordx4 v140, s[6:7]
	s_mov_b32 m0, s29
	v_mov_b32_e32 v143, v145
	global_load_lds_dwordx4 v142, s[6:7]
	s_mov_b32 s3, 0
	v_lshl_add_u64 v[6:7], s[18:19], 0, v[140:141]
	v_lshl_add_u64 v[4:5], s[18:19], 0, v[142:143]
	v_lshl_add_u64 v[2:3], s[16:17], 0, v[140:141]
	s_cmp_lg_u32 s4, 1
	v_lshl_add_u64 v[0:1], s[16:17], 0, v[142:143]
	v_readlane_b32 s14, v254, 4
	v_readlane_b32 s15, v254, 5
	s_cbranch_scc1 .LBB0_1245
	s_barrier
.LBB0_1245:
	v_readlane_b32 s6, v254, 0
	s_nop 0
	s_cmpk_gt_u32 s6, 63
	s_mov_b64 s[6:7], 0x80
	s_cselect_b32 s51, 0x58, 22
	s_cselect_b32 s2, -1, s2
	s_lshl_b32 s30, s4, 6
	s_lshl_b32 s10, s4, 13
	s_lshl_b32 s4, s5, 5
	s_add_i32 m0, s26, 0x18000
	v_lshl_add_u64 v[6:7], v[6:7], 0, s[6:7]
	s_and_b32 s31, s4, 0x60
	s_waitcnt vmcnt(4)
	s_barrier
	global_load_lds_dwordx4 v[6:7], off
	v_lshl_add_u64 v[4:5], v[4:5], 0, s[6:7]
	s_add_i32 m0, s26, 0x1a000
	s_add_i32 s33, s26, 0x8000
	s_add_i32 s34, s26, 0xa000
	global_load_lds_dwordx4 v[4:5], off
	v_lshl_add_u64 v[2:3], v[2:3], 0, s[6:7]
	s_mov_b32 m0, s33
	s_add_u32 s4, s18, 0x160080
	global_load_lds_dwordx4 v[2:3], off
	v_lshl_add_u64 v[0:1], v[0:1], 0, s[6:7]
	s_mov_b32 m0, s34
	s_addc_u32 s5, s19, 0
	global_load_lds_dwordx4 v[0:1], off
	s_add_i32 m0, s26, 0x1c000
	v_lshl_add_u64 v[0:1], s[4:5], 0, v[140:141]
	global_load_lds_dwordx4 v[0:1], off
	v_lshl_add_u64 v[0:1], s[4:5], 0, v[142:143]
	s_add_i32 m0, s26, 0x1e000
	v_lshl_or_b32 v158, s31, 7, v214
	global_load_lds_dwordx4 v[0:1], off
	v_lshlrev_b32_e32 v1, 2, v169
	v_lshl_or_b32 v0, v169, 6, v213
	v_and_b32_e32 v1, 32, v1
	s_waitcnt vmcnt(6)
	v_bitop3_b32 v0, v0, s10, v1 bitop3:0xde
	s_add_i32 s35, 0, 0x10000
	s_add_i32 s36, 0, 0x14000
	v_add3_u32 v146, v9, v211, v212
	v_mov_b32_e32 v147, v145
	v_add3_u32 v148, v8, v211, v212
	v_mov_b32_e32 v149, v145
	v_add_u32_e32 v159, s35, v158
	v_add_u32_e32 v160, 0, v0
	v_add_u32_e32 v161, s36, v158
	s_mov_b32 s37, 0x20000
	s_mov_b32 s38, 0x40000
	s_mov_b32 s39, 0x60000
	s_mov_b32 s40, 0x100000
	s_mov_b32 s41, 0x120000
	s_mov_b32 s42, 0x140000
	s_mov_b32 s43, 0x160000
	s_mov_b32 s44, s3
	s_barrier
	s_branch .LBB0_1247

.LBB0_1247:
	s_add_i32 s44, s44, 1
	s_mul_i32 s20, s44, s76
	v_readlane_b32 s4, v254, 0
	s_add_i32 s20, s20, s4
	s_cmpk_lt_u32 s4, 64
	s_cselect_b32 s14, 0x100, 0
	s_xor_b32 s20, s20, s14
	s_cmpk_lt_i32 s20, 0x140
	s_cselect_b64 s[14:15], -1, 0
	s_cmpk_gt_i32 s20, 0x13f
	s_cselect_b64 s[10:11], -1, 0
	s_and_b64 vcc, exec, s[10:11]
	s_cbranch_vccnz .LBB0_1253
	s_cmpk_lt_i32 s20, 0x100
	s_cselect_b64 s[4:5], -1, 0
	s_and_b64 s[12:13], s[4:5], exec
	s_cselect_b32 s12, s20, 0
	s_ashr_i32 s13, s12, 31
	s_lshr_b32 s13, s13, 29
	s_add_i32 s21, s12, s13
	s_and_b32 s13, s21, -8
	s_sub_i32 s45, s12, s13
	s_cmp_gt_i32 s45, -1
	s_mov_b64 s[12:13], -1
	s_cbranch_scc0 .LBB0_1250
	s_lshl_b32 s46, s45, 5
	s_mov_b64 s[12:13], 0

.LBB0_1270:
	v_mul_hi_i32 v1, v0, s11
	v_add_u32_e32 v1, v1, v0
	v_lshrrev_b32_e32 v2, 31, v1
	v_ashrrev_i32_e32 v1, 12, v1
	v_add_u32_e32 v2, v1, v2
	v_mad_i32_i24 v4, v2, s12, v0
	v_ashrrev_i32_e32 v3, 31, v2
	v_lshlrev_b64 v[6:7], 17, v[2:3]
	v_ashrrev_i32_e32 v5, 31, v4
	v_lshl_add_u64 v[2:3], s[40:41], 0, v[6:7]
	v_lshlrev_b64 v[8:9], 4, v[4:5]
	v_lshl_add_u64 v[2:3], v[2:3], 0, v[8:9]
	v_add_co_u32_e32 v2, vcc, s13, v2
	v_lshl_add_u64 v[12:13], s[42:43], 0, v[6:7]
	s_nop 0
	v_addc_co_u32_e32 v3, vcc, 0, v3, vcc
	global_load_dwordx4 v[2:5], v[2:3], off nt
	v_lshl_add_u64 v[10:11], s[2:3], 0, v[6:7]
	v_lshl_add_u64 v[12:13], v[12:13], 0, v[8:9]
	v_lshl_add_u64 v[10:11], v[10:11], 0, v[8:9]
	v_add_co_u32_e32 v12, vcc, 0x1000, v12
	v_add_u32_e32 v0, s10, v0
	s_nop 0
	v_addc_co_u32_e32 v13, vcc, 0, v13, vcc
	v_cmp_lt_i32_e32 vcc, s14, v0
	v_lshl_add_u64 v[6:7], s[4:5], 0, v[6:7]
	s_or_b64 s[6:7], vcc, s[6:7]
	v_lshl_add_u64 v[6:7], v[6:7], 0, v[8:9]
	s_waitcnt vmcnt(0)
	global_store_dwordx4 v[10:11], v[2:5], off nt
	global_load_dwordx4 v[2:5], v[12:13], off nt
	s_waitcnt vmcnt(0)
	global_store_dwordx4 v[6:7], v[2:5], off nt
	s_andn2_b64 exec, exec, s[6:7]
	s_cbranch_execnz .LBB0_1270
